# nt (non-temporal) cache policy on the once-read f32 input loads of the prologue
# speedup vs baseline: 1.0291x; 1.0097x over previous
.LBB0_9:
	s_add_i32 s16, s10, 0xffffc000
	s_cmpk_lt_i32 s10, 0x4000
	s_cselect_b32 s27, s11, 0
	s_cselect_b32 s26, s10, s16
	s_waitcnt lgkmcnt(0)
	s_cselect_b32 s36, s13, s15
	s_cselect_b32 s37, s12, s14
	s_lshl_b64 s[26:27], s[26:27], 12
	s_add_u32 s26, s37, s26
	s_addc_u32 s27, s36, s27
	global_load_dwordx4 v[34:37], v32, s[26:27] nt
	global_load_dwordx4 v[38:41], v32, s[26:27] offset:1024 nt
	global_load_dwordx4 v[42:45], v32, s[26:27] offset:2048 nt
	global_load_dwordx4 v[46:49], v32, s[26:27] offset:3072 nt
	s_add_u32 s26, s10, 1
	s_addc_u32 s27, s11, 0
	s_cmpk_gt_i32 s26, 0x3fff
	s_cselect_b64 s[38:39], -1, 0
	s_add_i32 s36, s10, 0xffffc001
	s_cmpk_lt_i32 s26, 0x4000
	s_cselect_b32 s27, s27, 0
	s_cselect_b32 s26, s26, s36
	s_cselect_b32 s37, s13, s15
	s_cselect_b32 s40, s12, s14
	s_lshl_b64 s[26:27], s[26:27], 12
	s_add_u32 s26, s40, s26
	s_addc_u32 s27, s37, s27
	global_load_dwordx4 v[14:17], v32, s[26:27] nt
	global_load_dwordx4 v[10:13], v32, s[26:27] offset:1024 nt
	global_load_dwordx4 v[6:9], v32, s[26:27] offset:2048 nt
	global_load_dwordx4 v[2:5], v32, s[26:27] offset:3072 nt
	s_mov_b32 s37, s17
	s_cmpk_gt_i32 s10, 0x3fff
	s_mov_b64 s[40:41], -1
	s_waitcnt vmcnt(7)
	v_mul_f32_e32 v24, v35, v35
	v_mul_f32_e32 v25, v37, v37
	s_waitcnt vmcnt(6)
	v_mul_f32_e32 v33, v39, v39
	v_mul_f32_e32 v50, v41, v41
	s_waitcnt vmcnt(5)
	v_mul_f32_e32 v51, v43, v43
	v_mul_f32_e32 v52, v45, v45
	v_fmac_f32_e32 v24, v34, v34
	v_fmac_f32_e32 v25, v36, v36
	v_fmac_f32_e32 v33, v38, v38
	v_fmac_f32_e32 v50, v40, v40
	s_waitcnt vmcnt(4)
	v_mul_f32_e32 v53, v47, v47
	v_mul_f32_e32 v54, v49, v49
	v_fmac_f32_e32 v51, v42, v42
	v_fmac_f32_e32 v52, v44, v44
	v_add_f32_e32 v24, v24, v25
	v_add_f32_e32 v25, v33, v50
	v_fmac_f32_e32 v53, v46, v46
	v_fmac_f32_e32 v54, v48, v48
	v_add_f32_e32 v33, v51, v52
	v_add_f32_e32 v24, v24, v25
	v_add_f32_e32 v50, v53, v54
	v_add_f32_e32 v24, v24, v33
	v_add_f32_e32 v24, v24, v50
	ds_bpermute_b32 v25, v26, v24
	v_cvt_pk_bf16_f32 v34, v34, v35
	v_cvt_pk_bf16_f32 v35, v36, v37
	v_cvt_pk_bf16_f32 v36, v38, v39
	v_cvt_pk_bf16_f32 v38, v42, v43
	s_waitcnt lgkmcnt(0)
	v_add_f32_e32 v33, v24, v25
	ds_bpermute_b32 v50, v27, v33
	v_lshl_add_u64 v[24:25], s[30:31], 0, v[20:21]
	v_cvt_pk_bf16_f32 v37, v40, v41
	v_cvt_pk_bf16_f32 v39, v44, v45
	v_cvt_pk_bf16_f32 v40, v46, v47
	s_waitcnt lgkmcnt(0)
	v_add_f32_e32 v33, v33, v50
	ds_bpermute_b32 v52, v28, v33
	v_add_co_u32_e32 v50, vcc, s42, v24
	v_cvt_pk_bf16_f32 v41, v48, v49
	s_nop 0
	v_addc_co_u32_e32 v51, vcc, 0, v25, vcc
	s_waitcnt lgkmcnt(0)
	v_add_f32_e32 v33, v33, v52
	ds_bpermute_b32 v52, v29, v33
	global_store_dwordx2 v[50:51], v[34:35], off offset:2048
	global_store_dwordx2 v[50:51], v[36:37], off offset:2560
	global_store_dwordx2 v[50:51], v[38:39], off offset:3072
	global_store_dwordx2 v[50:51], v[40:41], off offset:3584
	s_waitcnt lgkmcnt(0)
	v_add_f32_e32 v33, v33, v52
	ds_bpermute_b32 v52, v30, v33
	s_waitcnt lgkmcnt(0)
	v_add_f32_e32 v33, v33, v52
	ds_bpermute_b32 v42, v31, v33
	s_waitcnt lgkmcnt(0)
	v_add_f32_e32 v33, v33, v42
	s_cbranch_scc0 .LBB0_13
	s_and_saveexec_b64 s[40:41], s[4:5]
	s_cbranch_execz .LBB0_12
	s_lshl_b64 s[26:27], s[16:17], 7
	v_lshl_add_u64 v[34:35], v[18:19], 0, s[26:27]
	v_cndmask_b32_e64 v36, 0, v33, s[6:7]
	global_store_dword v[34:35], v36, off

.LBB0_53:
	s_lshr_b32 s6, s36, 6
	v_cvt_f32_u32_e32 v8, s6
	s_sub_i32 s27, 0, s6
	s_abs_i32 s26, s66
	s_ashr_i32 s7, s66, 31
	v_rcp_iflag_f32_e32 v8, v8
	s_mul_i32 s82, s36, 9
	s_mul_i32 s86, s36, 62
	s_mov_b32 s87, s37
	v_mul_f32_e32 v8, 0x4f7ffffe, v8
	v_cvt_u32_f32_e32 v8, v8
	s_mov_b32 s83, s37
	v_readfirstlane_b32 s67, v8
	s_mul_i32 s27, s27, s67
	s_mul_hi_u32 s27, s67, s27
	s_add_i32 s67, s67, s27
	s_mul_hi_u32 s27, s26, s67
	s_mul_i32 s67, s27, s6
	s_sub_i32 s26, s26, s67
	s_add_i32 s73, s27, 1
	s_sub_i32 s67, s26, s6
	s_cmp_ge_u32 s26, s6
	s_cselect_b32 s27, s73, s27
	s_cselect_b32 s26, s67, s26
	s_add_i32 s67, s27, 1
	s_cmp_ge_u32 s26, s6
	s_cselect_b32 s26, s67, s27
	s_xor_b32 s26, s26, s7
	s_sub_i32 s7, s26, s7
	s_mul_i32 s26, s7, s6
	s_lshl_b32 s6, s7, 6
	s_ashr_i32 s7, s6, 31
	s_sub_i32 s73, s66, s26
	s_mul_hi_u32 s26, s6, s36
	s_mul_i32 s27, s7, s36
	s_add_i32 s27, s26, s27
	s_mul_i32 s26, s6, s36
	s_lshl_b32 s66, s73, 6
	s_lshl_b64 s[26:27], s[26:27], 2
	s_add_u32 s70, s70, s26
	s_addc_u32 s71, s71, s27
	s_ashr_i32 s67, s66, 31
	s_lshl_b64 s[26:27], s[66:67], 2
	s_add_u32 s70, s70, s26
	s_addc_u32 s71, s71, s27
	v_lshl_add_u64 v[50:51], s[70:71], 0, v[4:5]
	s_lshl_b32 s26, s36, 1
	s_mov_b32 s27, s37
	v_lshl_add_u64 v[52:53], s[26:27], 2, v[50:51]
	s_mul_i32 s26, s36, 3
	v_lshl_add_u64 v[54:55], s[26:27], 2, v[50:51]
	s_lshl_b32 s26, s36, 2
	v_lshl_add_u64 v[68:69], s[26:27], 2, v[50:51]
	s_mul_i32 s26, s36, 5
	v_lshl_add_u64 v[70:71], s[26:27], 2, v[50:51]
	s_mul_i32 s26, s36, 6
	v_lshl_add_u64 v[72:73], s[26:27], 2, v[50:51]
	s_mul_i32 s26, s36, 7
	v_lshl_add_u64 v[74:75], s[26:27], 2, v[50:51]
	s_mul_i32 s26, s36, 10
	v_lshl_add_u64 v[56:57], s[26:27], 2, v[50:51]
	s_mul_i32 s26, s36, 11
	v_lshl_add_u64 v[58:59], s[26:27], 2, v[50:51]
	s_mul_i32 s26, s36, 12
	v_lshl_add_u64 v[60:61], s[26:27], 2, v[50:51]
	s_mul_i32 s26, s36, 13
	v_lshl_add_u64 v[62:63], s[26:27], 2, v[50:51]
	s_mul_i32 s26, s36, 14
	v_lshl_add_u64 v[64:65], s[26:27], 2, v[50:51]
	s_mul_i32 s26, s36, 15
	v_lshl_add_u64 v[76:77], s[26:27], 2, v[50:51]
	s_lshl_b32 s26, s36, 4
	v_lshl_add_u64 v[78:79], s[26:27], 2, v[50:51]
	s_mul_i32 s26, s36, 17
	v_lshl_add_u64 v[8:9], s[26:27], 2, v[50:51]
	s_mul_i32 s26, s36, 18
	v_lshl_add_u64 v[10:11], s[26:27], 2, v[50:51]
	s_mul_i32 s26, s36, 19
	v_lshl_add_u64 v[12:13], s[26:27], 2, v[50:51]
	s_mul_i32 s26, s36, 20
	v_lshl_add_u64 v[14:15], s[26:27], 2, v[50:51]
	s_mul_i32 s26, s36, 21
	v_lshl_add_u64 v[16:17], s[26:27], 2, v[50:51]
	s_mul_i32 s26, s36, 22
	v_lshl_add_u64 v[18:19], s[26:27], 2, v[50:51]
	s_mul_i32 s26, s36, 23
	v_lshl_add_u64 v[20:21], s[26:27], 2, v[50:51]
	s_mul_i32 s26, s36, 24
	v_lshl_add_u64 v[22:23], s[26:27], 2, v[50:51]
	s_mul_i32 s26, s36, 25
	global_load_dword v9, v[8:9], off nt
	s_nop 0
	global_load_dword v10, v[10:11], off nt
	s_nop 0
	global_load_dword v11, v[12:13], off nt
	s_nop 0
	global_load_dword v12, v[14:15], off nt
	global_load_dword v13, v[16:17], off nt
	s_nop 0
	global_load_dword v14, v[18:19], off nt
	global_load_dword v15, v[20:21], off nt
	global_load_dword v16, v[22:23], off nt
	v_lshl_add_u64 v[18:19], s[26:27], 2, v[50:51]
	s_mul_i32 s26, s36, 26
	v_lshl_add_u64 v[20:21], s[26:27], 2, v[50:51]
	s_mul_i32 s26, s36, 27
	v_lshl_add_u64 v[22:23], s[26:27], 2, v[50:51]
	s_mul_i32 s26, s36, 28
	v_lshl_add_u64 v[24:25], s[26:27], 2, v[50:51]
	s_mul_i32 s26, s36, 29
	v_lshl_add_u64 v[26:27], s[26:27], 2, v[50:51]
	s_mul_i32 s26, s36, 30
	v_lshl_add_u64 v[28:29], s[26:27], 2, v[50:51]
	s_mul_i32 s26, s36, 31
	v_lshl_add_u64 v[30:31], s[26:27], 2, v[50:51]
	s_lshl_b32 s26, s36, 5
	v_lshl_add_u64 v[32:33], s[26:27], 2, v[50:51]
	s_mul_i32 s26, s36, 33
	global_load_dword v17, v[18:19], off nt
	s_nop 0
	global_load_dword v18, v[20:21], off nt
	global_load_dword v19, v[22:23], off nt
	s_nop 0
	global_load_dword v20, v[24:25], off nt
	global_load_dword v21, v[26:27], off nt
	global_load_dword v22, v[28:29], off nt
	global_load_dword v23, v[30:31], off nt
	s_nop 0
	global_load_dword v24, v[32:33], off nt
	v_lshl_add_u64 v[26:27], s[26:27], 2, v[50:51]
	s_mul_i32 s26, s36, 34
	v_lshl_add_u64 v[28:29], s[26:27], 2, v[50:51]
	s_mul_i32 s26, s36, 35
	v_lshl_add_u64 v[30:31], s[26:27], 2, v[50:51]
	s_mul_i32 s26, s36, 36
	v_lshl_add_u64 v[32:33], s[26:27], 2, v[50:51]
	s_mul_i32 s26, s36, 37
	v_lshl_add_u64 v[34:35], s[26:27], 2, v[50:51]
	s_mul_i32 s26, s36, 38
	v_lshl_add_u64 v[36:37], s[26:27], 2, v[50:51]
	s_mul_i32 s26, s36, 39
	v_lshl_add_u64 v[38:39], s[26:27], 2, v[50:51]
	s_mul_i32 s26, s36, 40
	v_lshl_add_u64 v[40:41], s[26:27], 2, v[50:51]
	s_mul_i32 s26, s36, 41
	global_load_dword v25, v[26:27], off nt
	s_nop 0
	global_load_dword v26, v[28:29], off nt
	global_load_dword v27, v[30:31], off nt
	s_nop 0
	global_load_dword v28, v[32:33], off nt
	global_load_dword v29, v[34:35], off nt
	global_load_dword v30, v[36:37], off nt
	global_load_dword v31, v[38:39], off nt
	s_nop 0
	global_load_dword v32, v[40:41], off nt
	v_lshl_add_u64 v[34:35], s[26:27], 2, v[50:51]
	s_mul_i32 s26, s36, 42
	v_lshl_add_u64 v[36:37], s[26:27], 2, v[50:51]
	s_mul_i32 s26, s36, 43
	v_lshl_add_u64 v[38:39], s[26:27], 2, v[50:51]
	s_mul_i32 s26, s36, 44
	v_lshl_add_u64 v[40:41], s[26:27], 2, v[50:51]
	s_mul_i32 s26, s36, 45
	v_lshl_add_u64 v[42:43], s[26:27], 2, v[50:51]
	s_mul_i32 s26, s36, 46
	v_lshl_add_u64 v[44:45], s[26:27], 2, v[50:51]
	s_mul_i32 s26, s36, 47
	v_lshl_add_u64 v[46:47], s[26:27], 2, v[50:51]
	s_mul_i32 s26, s36, 48
	v_lshl_add_u64 v[48:49], s[26:27], 2, v[50:51]
	s_mul_i32 s26, s36, 49
	global_load_dword v33, v[34:35], off nt
	s_nop 0
	global_load_dword v34, v[36:37], off nt
	global_load_dword v35, v[38:39], off nt
	s_nop 0
	global_load_dword v36, v[40:41], off nt
	global_load_dword v37, v[42:43], off nt
	global_load_dword v38, v[44:45], off nt
	global_load_dword v39, v[46:47], off nt
	s_nop 0
	global_load_dword v40, v[48:49], off nt
	v_lshl_add_u64 v[42:43], s[26:27], 2, v[50:51]
	s_mul_i32 s26, s36, 50
	v_lshl_add_u64 v[44:45], s[26:27], 2, v[50:51]
	s_mul_i32 s26, s36, 51
	v_lshl_add_u64 v[46:47], s[26:27], 2, v[50:51]
	s_mul_i32 s26, s36, 52
	v_lshl_add_u64 v[48:49], s[26:27], 2, v[50:51]
	s_mul_i32 s26, s36, 53
	v_lshl_add_u64 v[88:89], s[26:27], 2, v[50:51]
	s_mul_i32 s26, s36, 54
	v_lshl_add_u64 v[90:91], s[26:27], 2, v[50:51]
	s_mul_i32 s26, s36, 55
	v_lshl_add_u64 v[92:93], s[26:27], 2, v[50:51]
	s_mul_i32 s26, s36, 56
	v_lshl_add_u64 v[94:95], s[26:27], 2, v[50:51]
	s_mul_i32 s26, s36, 57
	global_load_dword v41, v[42:43], off nt
	s_nop 0
	global_load_dword v42, v[44:45], off nt
	global_load_dword v43, v[46:47], off nt
	s_nop 0
	global_load_dword v44, v[48:49], off nt
	global_load_dword v45, v[88:89], off nt
	global_load_dword v46, v[90:91], off nt
	global_load_dword v47, v[92:93], off nt
	s_nop 0
	global_load_dword v48, v[94:95], off nt
	v_lshl_add_u64 v[88:89], s[26:27], 2, v[50:51]
	s_mul_i32 s26, s36, 58
	v_lshl_add_u64 v[90:91], s[26:27], 2, v[50:51]
	s_mul_i32 s26, s36, 59
	v_lshl_add_u64 v[92:93], s[26:27], 2, v[50:51]
	s_mul_i32 s26, s36, 60
	v_lshl_add_u64 v[94:95], s[26:27], 2, v[50:51]
	s_mul_i32 s26, s36, 61
	v_lshl_add_u64 v[96:97], s[26:27], 2, v[50:51]
	s_lshl_b32 s26, s36, 3
	v_lshl_add_u64 v[100:101], s[36:37], 2, v[50:51]
	s_mul_i32 s36, s36, 63
	v_lshl_add_u64 v[98:99], s[86:87], 2, v[50:51]
	v_lshl_add_u64 v[102:103], s[36:37], 2, v[50:51]
	v_lshl_add_u64 v[104:105], s[82:83], 2, v[50:51]
	v_lshl_add_u64 v[50:51], s[26:27], 2, v[50:51]
	global_load_dword v56, v[56:57], off nt
	s_nop 0
	global_load_dword v57, v[58:59], off nt
	s_nop 0
	global_load_dword v58, v[60:61], off nt
	global_load_dword v59, v[62:63], off nt
	s_nop 0
	global_load_dword v60, v[64:65], off nt
	global_load_dword v61, v[76:77], off nt
	global_load_dword v8, v[78:79], off nt
	global_load_dword v63, v[104:105], off nt
	s_nop 0
	global_load_dword v64, v[52:53], off nt
	global_load_dword v65, v[54:55], off nt
	s_nop 0
	global_load_dword v68, v[68:69], off nt
	s_nop 0
	global_load_dword v69, v[70:71], off nt
	s_nop 0
	global_load_dword v70, v[72:73], off nt
	global_load_dword v71, v[74:75], off nt
	global_load_dword v62, v[50:51], off nt
	s_nop 0
	global_load_dword v73, v[100:101], off nt
	global_load_dword v49, v[88:89], off nt
	global_load_dword v50, v[90:91], off nt
	global_load_dword v51, v[92:93], off nt
	global_load_dword v52, v[94:95], off nt
	global_load_dword v53, v[96:97], off nt
	global_load_dword v54, v[98:99], off nt
	global_load_dword v55, v[102:103], off nt
	global_load_dword v72, v4, s[70:71] nt
	s_cmp_eq_u64 s[68:69], 0
	s_cbranch_scc1 .LBB0_55
	s_lshl_b64 s[26:27], s[6:7], 2
	s_add_u32 s68, s68, s26
	s_addc_u32 s69, s69, s27
	global_load_dwordx4 v[74:77], v3, s[68:69] nt
	global_load_dwordx4 v[88:91], v3, s[68:69] offset:16 nt
	global_load_dwordx4 v[92:95], v3, s[68:69] offset:32 nt
	global_load_dwordx4 v[96:99], v3, s[68:69] offset:48 nt
	global_load_dwordx4 v[100:103], v3, s[68:69] offset:64 nt
	global_load_dwordx4 v[104:107], v3, s[68:69] offset:80 nt
	global_load_dwordx4 v[108:111], v3, s[68:69] offset:96 nt
	global_load_dwordx4 v[112:115], v3, s[68:69] offset:112 nt
	global_load_dwordx4 v[116:119], v3, s[68:69] offset:128 nt
	global_load_dwordx4 v[120:123], v3, s[68:69] offset:144 nt
	global_load_dwordx4 v[124:127], v3, s[68:69] offset:160 nt
	global_load_dwordx4 v[128:131], v3, s[68:69] offset:176 nt
	global_load_dwordx4 v[132:135], v3, s[68:69] offset:192 nt
	global_load_dwordx4 v[136:139], v3, s[68:69] offset:208 nt
	global_load_dwordx4 v[140:143], v3, s[68:69] offset:224 nt
	global_load_dwordx4 v[144:147], v3, s[68:69] offset:240 nt
	s_waitcnt vmcnt(15)
	v_pk_mul_f32 v[72:73], v[72:73], v[74:75]
	v_pk_mul_f32 v[64:65], v[64:65], v[76:77]
	s_waitcnt vmcnt(14)
	v_pk_mul_f32 v[68:69], v[68:69], v[88:89]
	v_pk_mul_f32 v[70:71], v[70:71], v[90:91]
	s_waitcnt vmcnt(13)
	v_pk_mul_f32 v[62:63], v[62:63], v[92:93]
	v_pk_mul_f32 v[56:57], v[56:57], v[94:95]
	s_waitcnt vmcnt(12)
	v_pk_mul_f32 v[58:59], v[58:59], v[96:97]
	v_pk_mul_f32 v[60:61], v[60:61], v[98:99]
	s_waitcnt vmcnt(11)
	v_pk_mul_f32 v[8:9], v[8:9], v[100:101]
	v_pk_mul_f32 v[10:11], v[10:11], v[102:103]
	s_waitcnt vmcnt(10)
	v_pk_mul_f32 v[12:13], v[12:13], v[104:105]
	v_pk_mul_f32 v[14:15], v[14:15], v[106:107]
	s_waitcnt vmcnt(9)
	v_pk_mul_f32 v[16:17], v[16:17], v[108:109]
	v_pk_mul_f32 v[18:19], v[18:19], v[110:111]
	s_waitcnt vmcnt(8)
	v_pk_mul_f32 v[20:21], v[20:21], v[112:113]
	v_pk_mul_f32 v[22:23], v[22:23], v[114:115]
	s_waitcnt vmcnt(7)
	v_pk_mul_f32 v[24:25], v[24:25], v[116:117]
	v_pk_mul_f32 v[26:27], v[26:27], v[118:119]
	s_waitcnt vmcnt(6)
	v_pk_mul_f32 v[28:29], v[28:29], v[120:121]
	v_pk_mul_f32 v[30:31], v[30:31], v[122:123]
	s_waitcnt vmcnt(5)
	v_pk_mul_f32 v[32:33], v[32:33], v[124:125]
	v_pk_mul_f32 v[34:35], v[34:35], v[126:127]
	s_waitcnt vmcnt(4)
	v_pk_mul_f32 v[36:37], v[36:37], v[128:129]
	v_pk_mul_f32 v[38:39], v[38:39], v[130:131]
	s_waitcnt vmcnt(3)
	v_pk_mul_f32 v[40:41], v[40:41], v[132:133]
	v_pk_mul_f32 v[42:43], v[42:43], v[134:135]
	s_waitcnt vmcnt(2)
	v_pk_mul_f32 v[44:45], v[44:45], v[136:137]
	v_pk_mul_f32 v[46:47], v[46:47], v[138:139]
	s_waitcnt vmcnt(1)
	v_pk_mul_f32 v[48:49], v[48:49], v[140:141]
	v_pk_mul_f32 v[50:51], v[50:51], v[142:143]
	s_waitcnt vmcnt(0)
	v_pk_mul_f32 v[52:53], v[52:53], v[144:145]
	v_pk_mul_f32 v[54:55], v[54:55], v[146:147]

.LBB0_120:
	v_add_u32_e32 v18, s15, v14
	v_mad_i64_i32 v[24:25], s[20:21], v18, s16, v[12:13]
	global_load_dword v15, v[24:25], off nt
	s_and_b64 vcc, exec, s[4:5]
	v_ashrrev_i32_e32 v19, 31, v18
	s_cbranch_vccnz .LBB0_122
	v_lshl_add_u64 v[24:25], v[18:19], 2, s[6:7]
	global_load_dword v19, v[24:25], off nt
	s_waitcnt vmcnt(0)
	v_mul_f32_e32 v15, v15, v19
.LBB0_122:
	v_add_u32_e32 v19, 2, v18
	v_mad_i64_i32 v[24:25], s[20:21], v19, s16, v[12:13]
	global_load_dword v19, v[24:25], off nt
	s_and_b64 vcc, exec, s[4:5]
	s_waitcnt vmcnt(1)
	ds_write_b32 v4, v15
	s_cbranch_vccnz .LBB0_124
	global_load_dword v15, v[16:17], off offset:-112 nt
	s_waitcnt vmcnt(0)
	v_mul_f32_e32 v19, v19, v15
.LBB0_124:
	v_add_u32_e32 v15, 4, v18
	v_mad_i64_i32 v[24:25], s[20:21], v15, s16, v[12:13]
	global_load_dword v15, v[24:25], off nt
	s_and_b64 vcc, exec, s[4:5]
	s_waitcnt vmcnt(1)
	ds_write_b32 v4, v19 offset:264
	s_cbranch_vccnz .LBB0_126
	global_load_dword v19, v[16:17], off offset:-104 nt
	s_waitcnt vmcnt(0)
	v_mul_f32_e32 v15, v15, v19
.LBB0_126:
	v_add_u32_e32 v19, 6, v18
	v_mad_i64_i32 v[24:25], s[20:21], v19, s16, v[12:13]
	global_load_dword v19, v[24:25], off nt
	s_and_b64 vcc, exec, s[4:5]
	s_waitcnt vmcnt(1)
	ds_write_b32 v4, v15 offset:528
	s_cbranch_vccnz .LBB0_128
	global_load_dword v15, v[16:17], off offset:-96 nt
	s_waitcnt vmcnt(0)
	v_mul_f32_e32 v19, v19, v15
.LBB0_128:
	v_add_u32_e32 v15, 8, v18
	v_mad_i64_i32 v[24:25], s[20:21], v15, s16, v[12:13]
	global_load_dword v15, v[24:25], off nt
	s_and_b64 vcc, exec, s[4:5]
	s_waitcnt vmcnt(1)
	ds_write_b32 v4, v19 offset:792
	s_cbranch_vccnz .LBB0_130
	global_load_dword v19, v[16:17], off offset:-88 nt
	s_waitcnt vmcnt(0)
	v_mul_f32_e32 v15, v15, v19
.LBB0_130:
	v_add_u32_e32 v19, 10, v18
	v_mad_i64_i32 v[24:25], s[20:21], v19, s16, v[12:13]
	global_load_dword v19, v[24:25], off nt
	s_and_b64 vcc, exec, s[4:5]
	s_waitcnt vmcnt(1)
	ds_write_b32 v4, v15 offset:1056
	s_cbranch_vccnz .LBB0_132
	global_load_dword v15, v[16:17], off offset:-80 nt
	s_waitcnt vmcnt(0)
	v_mul_f32_e32 v19, v19, v15
.LBB0_132:
	v_add_u32_e32 v15, 12, v18
	v_mad_i64_i32 v[24:25], s[20:21], v15, s16, v[12:13]
	global_load_dword v15, v[24:25], off nt
	s_and_b64 vcc, exec, s[4:5]
	s_waitcnt vmcnt(1)
	ds_write_b32 v4, v19 offset:1320
	s_cbranch_vccnz .LBB0_134
	global_load_dword v19, v[16:17], off offset:-72 nt
	s_waitcnt vmcnt(0)
	v_mul_f32_e32 v15, v15, v19
.LBB0_134:
	v_add_u32_e32 v19, 14, v18
	v_mad_i64_i32 v[24:25], s[20:21], v19, s16, v[12:13]
	global_load_dword v19, v[24:25], off nt
	s_and_b64 vcc, exec, s[4:5]
	s_waitcnt vmcnt(1)
	ds_write_b32 v4, v15 offset:1584
	s_cbranch_vccnz .LBB0_136
	global_load_dword v15, v[16:17], off offset:-64 nt
	s_waitcnt vmcnt(0)
	v_mul_f32_e32 v19, v19, v15
.LBB0_136:
	v_add_u32_e32 v15, 16, v18
	v_mad_i64_i32 v[24:25], s[20:21], v15, s16, v[12:13]
	global_load_dword v15, v[24:25], off nt
	s_and_b64 vcc, exec, s[4:5]
	s_waitcnt vmcnt(1)
	ds_write_b32 v4, v19 offset:1848
	s_cbranch_vccnz .LBB0_138
	global_load_dword v19, v[16:17], off offset:-56 nt
	s_waitcnt vmcnt(0)
	v_mul_f32_e32 v15, v15, v19
.LBB0_138:
	v_add_u32_e32 v19, 18, v18
	v_mad_i64_i32 v[24:25], s[20:21], v19, s16, v[12:13]
	global_load_dword v19, v[24:25], off nt
	s_and_b64 vcc, exec, s[4:5]
	s_waitcnt vmcnt(1)
	ds_write_b32 v4, v15 offset:2112
	s_cbranch_vccnz .LBB0_140
	global_load_dword v15, v[16:17], off offset:-48 nt
	s_waitcnt vmcnt(0)
	v_mul_f32_e32 v19, v19, v15
.LBB0_140:
	v_add_u32_e32 v15, 20, v18
	v_mad_i64_i32 v[24:25], s[20:21], v15, s16, v[12:13]
	global_load_dword v15, v[24:25], off nt
	s_and_b64 vcc, exec, s[4:5]
	s_waitcnt vmcnt(1)
	ds_write_b32 v4, v19 offset:2376
	s_cbranch_vccnz .LBB0_142
	global_load_dword v19, v[16:17], off offset:-40 nt
	s_waitcnt vmcnt(0)
	v_mul_f32_e32 v15, v15, v19
.LBB0_142:
	v_add_u32_e32 v19, 22, v18
	v_mad_i64_i32 v[24:25], s[20:21], v19, s16, v[12:13]
	global_load_dword v19, v[24:25], off nt
	s_and_b64 vcc, exec, s[4:5]
	s_waitcnt vmcnt(1)
	ds_write_b32 v4, v15 offset:2640
	s_cbranch_vccnz .LBB0_144
	global_load_dword v15, v[16:17], off offset:-32 nt
	s_waitcnt vmcnt(0)
	v_mul_f32_e32 v19, v19, v15
.LBB0_144:
	v_add_u32_e32 v15, 24, v18
	v_mad_i64_i32 v[24:25], s[20:21], v15, s16, v[12:13]
	global_load_dword v15, v[24:25], off nt
	s_and_b64 vcc, exec, s[4:5]
	s_waitcnt vmcnt(1)
	ds_write_b32 v4, v19 offset:2904
	s_cbranch_vccnz .LBB0_146
	global_load_dword v19, v[16:17], off offset:-24 nt
	s_waitcnt vmcnt(0)
	v_mul_f32_e32 v15, v15, v19
.LBB0_146:
	v_add_u32_e32 v19, 26, v18
	v_mad_i64_i32 v[24:25], s[20:21], v19, s16, v[12:13]
	global_load_dword v19, v[24:25], off nt
	s_and_b64 vcc, exec, s[4:5]
	s_waitcnt vmcnt(1)
	ds_write_b32 v4, v15 offset:3168
	s_cbranch_vccnz .LBB0_148
	global_load_dword v15, v[16:17], off offset:-16 nt
	s_waitcnt vmcnt(0)
	v_mul_f32_e32 v19, v19, v15
.LBB0_148:
	v_add_u32_e32 v15, 28, v18
	v_mad_i64_i32 v[24:25], s[20:21], v15, s16, v[12:13]
	global_load_dword v15, v[24:25], off nt
	s_and_b64 vcc, exec, s[4:5]
	s_waitcnt vmcnt(1)
	ds_write_b32 v4, v19 offset:3432
	s_cbranch_vccnz .LBB0_150
	global_load_dword v19, v[16:17], off offset:-8 nt
	s_waitcnt vmcnt(0)
	v_mul_f32_e32 v15, v15, v19
.LBB0_150:
	v_add_u32_e32 v18, 30, v18
	v_mad_i64_i32 v[18:19], s[20:21], v18, s16, v[12:13]
	global_load_dword v18, v[18:19], off nt
	s_and_b64 vcc, exec, s[4:5]
	s_waitcnt vmcnt(1)
	ds_write_b32 v4, v15 offset:3696
	s_cbranch_vccnz .LBB0_119
	global_load_dword v15, v[16:17], off nt
	s_waitcnt vmcnt(0)
	v_mul_f32_e32 v18, v18, v15
	s_branch .LBB0_119

.LBB0_157:
	s_waitcnt lgkmcnt(0)
	v_lshl_add_u64 v[6:7], s[4:5], 0, v[4:5]
	global_load_dwordx4 v[10:13], v[6:7], off nt
	s_ashr_i32 s11, s10, 7
	s_and_b32 s12, s10, 0x7f
	s_mul_hi_i32 s13, s11, 0xc0
	s_mulk_i32 s11, 0xc0
	s_add_u32 s12, s11, s12
	s_addc_u32 s13, s13, 0
	s_lshl_b64 s[12:13], s[12:13], 10
	v_lshl_add_u64 v[14:15], v[2:3], 0, s[12:13]
	v_lshl_add_u64 v[6:7], s[6:7], 0, v[4:5]
	s_add_i32 s10, s10, s38
	v_lshl_add_u64 v[4:5], v[4:5], 0, s[8:9]
	s_cmpk_gt_i32 s10, 0xfff
	s_waitcnt vmcnt(0)
	v_cvt_pk_bf16_f32 v10, v10, v11
	v_cvt_pk_bf16_f32 v11, v12, v13
	global_store_dwordx2 v[14:15], v[10:11], off
	global_load_dwordx4 v[10:13], v[6:7], off nt
	s_waitcnt vmcnt(0)
	v_cvt_pk_bf16_f32 v6, v10, v11
	v_cvt_pk_bf16_f32 v7, v12, v13
	global_store_dwordx2 v[14:15], v[6:7], off offset:512
	s_cbranch_scc0 .LBB0_157
.LBB0_158:
	s_mov_b32 s4, 0x10100
	v_cmp_gt_i32_e32 vcc, s4, v8
	s_and_saveexec_b64 s[12:13], vcc
	s_cbranch_execz .LBB0_169
	v_and_b32_e32 v2, 15, v1
	v_lshlrev_b32_e32 v2, 2, v2
	global_load_dword v12, v2, s[0:1] offset:256 nt
	v_mov_b32_e32 v3, 0
	v_lshl_add_u64 v[6:7], s[30:31], 0, v[2:3]
	s_mov_b64 s[4:5], 0x5810000
	v_lshl_add_u64 v[4:5], v[6:7], 0, s[4:5]
	s_mov_b64 s[4:5], 0x5810040
	s_lshl_b32 s20, s28, 9
	v_lshl_add_u64 v[6:7], v[6:7], 0, s[4:5]
	s_mov_b64 s[14:15], 0
	s_brev_b32 s21, 18
	s_mov_b32 s22, 0xfe5163ab
	s_mov_b32 s23, 0x3c439041
	s_mov_b32 s39, 0xdb629599
	s_mov_b32 s40, 0xf534ddc0
	s_mov_b32 s41, 0xfc2757d1
	s_mov_b32 s42, 0x4e441529
	s_mov_b32 s43, 0xa2f9836e
	s_mov_b32 s44, 0x3fc90fda
	s_mov_b32 s45, 0x3f22f983
	s_mov_b32 s46, 0xbfc90fda
	v_mov_b32_e32 v13, 0x3c0881c4
	v_mov_b32_e32 v14, 0xbab64f3b
	s_brev_b32 s47, 1
	s_movk_i32 s48, 0x1f8
	s_mov_b32 s49, 0x100ff
	v_not_b32_e32 v15, 63
	v_not_b32_e32 v16, 31
	v_mov_b32_e32 v17, 0x7fc00000
	v_mov_b32_e32 v18, v8
	s_waitcnt vmcnt(0)
	s_branch .LBB0_161

.LBB0_171:
	v_subrev_co_u32_sdwa v6, vcc, s13, v8 dst_sel:DWORD dst_unused:UNUSED_PAD src0_sel:DWORD src1_sel:BYTE_0
	s_mov_b64 s[4:5], vcc
	v_sub_co_u32_sdwa v7, vcc, s13, v8 dst_sel:DWORD dst_unused:UNUSED_PAD src0_sel:DWORD src1_sel:BYTE_0
	v_cndmask_b32_e64 v6, v6, v7, s[4:5]
	v_max_i32_e32 v7, 1, v6
	v_cvt_f32_u32_e32 v7, v7
	s_mov_b64 s[6:7], vcc
	v_ashrrev_i32_e32 v5, 8, v8
	v_add_u32_e32 v8, s12, v8
	v_mul_f32_e32 v7, 0x3e000000, v7
	v_cmp_gt_f32_e32 vcc, s20, v7
	s_nop 1
	v_cndmask_b32_e64 v9, 0, 32, vcc
	v_ldexp_f32 v7, v7, v9
	v_log_f32_e32 v7, v7
	v_cndmask_b32_e32 v9, 0, v4, vcc
	v_mul_f32_e32 v10, 0x3f317217, v7
	v_fma_f32 v10, v7, s21, -v10
	v_fmac_f32_e32 v10, 0x3377d1cf, v7
	v_fmac_f32_e32 v10, 0x3f317217, v7
	v_cmp_lt_f32_e64 vcc, |v7|, s22
	s_nop 1
	v_cndmask_b32_e32 v7, v7, v10, vcc
	v_sub_f32_e32 v7, v7, v9
	v_div_scale_f32 v9, s[4:5], s23, s23, v7
	v_rcp_f32_e32 v11, v9
	v_div_scale_f32 v10, vcc, v7, s23, v7
	v_fma_f32 v12, -v9, v11, 1.0
	v_fmac_f32_e32 v11, v12, v11
	v_mul_f32_e32 v12, v10, v11
	v_fma_f32 v13, -v9, v12, v10
	v_fmac_f32_e32 v12, v13, v11
	v_fma_f32 v9, -v9, v12, v10
	v_div_fmas_f32 v9, v9, v11, v12
	v_div_fixup_f32 v7, v9, s23, v7
	v_mul_f32_e32 v7, 0x41000000, v7
	v_cvt_i32_f32_e32 v7, v7
	v_cmp_gt_i32_e32 vcc, 8, v6
	v_cndmask_b32_e64 v9, 0, 16, s[6:7]
	v_min_i32_e32 v7, 7, v7
	v_add_u32_e32 v7, 8, v7
	v_cndmask_b32_e32 v6, v7, v6, vcc
	v_add_u32_e32 v6, v6, v9
	v_lshl_add_u32 v6, v6, 4, v5
	v_ashrrev_i32_e32 v7, 31, v6
	s_waitcnt lgkmcnt(0)
	v_lshl_add_u64 v[6:7], v[6:7], 2, s[10:11]
	global_load_dword v5, v[6:7], off nt
	v_cmp_lt_i32_e32 vcc, s26, v8
	s_or_b64 s[16:17], vcc, s[16:17]
	s_waitcnt vmcnt(0)
	v_mul_f32_e32 v5, 0x3fb8aa3b, v5
	global_store_dword v[2:3], v5, off
	v_lshl_add_u64 v[2:3], v[2:3], 0, s[14:15]
	s_andn2_b64 exec, exec, s[16:17]
	s_cbranch_execnz .LBB0_171

.LBB0_174:
	s_ashr_i32 s33, s61, 7
	s_lshl_b32 s4, s33, 6
	s_ashr_i32 s5, s4, 31
	s_lshl_b32 s26, s10, 13
	s_lshl_b32 s27, s61, 3
	v_lshl_add_u64 v[26:27], s[4:5], 2, v[52:53]
	s_and_b32 s62, s26, 0x780000
	s_and_b32 s26, s27, 0x3c0
	s_lshl_b64 s[4:5], s[4:5], 12
	v_or_b32_e32 v34, s26, v66
	s_add_u32 s4, s6, s4
	v_mov_b32_e32 v37, v51
	v_lshlrev_b32_e32 v36, 2, v34
	s_addc_u32 s5, s7, s5
	v_lshl_add_u64 v[34:35], s[4:5], 0, v[36:37]
	v_add_co_u32_e32 v38, vcc, s12, v34
	v_lshl_add_u64 v[2:3], v[26:27], 0, v[54:55]
	s_nop 0
	v_addc_co_u32_e32 v39, vcc, 0, v35, vcc
	v_add_co_u32_e32 v40, vcc, s13, v34
	v_lshl_add_u64 v[6:7], v[26:27], 0, v[56:57]
	s_nop 0
	v_addc_co_u32_e32 v41, vcc, 0, v35, vcc
	v_add_co_u32_e32 v42, vcc, s14, v34
	v_lshl_add_u64 v[10:11], v[26:27], 0, v[58:59]
	s_nop 0
	v_addc_co_u32_e32 v43, vcc, 0, v35, vcc
	v_add_co_u32_e32 v44, vcc, s15, v34
	v_lshl_add_u64 v[14:15], v[26:27], 0, v[60:61]
	s_nop 0
	v_addc_co_u32_e32 v45, vcc, 0, v35, vcc
	v_add_co_u32_e32 v46, vcc, s16, v34
	v_lshl_add_u64 v[18:19], v[26:27], 0, v[62:63]
	s_nop 0
	v_addc_co_u32_e32 v47, vcc, 0, v35, vcc
	v_add_co_u32_e32 v48, vcc, s17, v34
	v_lshl_add_u64 v[22:23], v[26:27], 0, v[64:65]
	s_nop 0
	v_addc_co_u32_e32 v49, vcc, 0, v35, vcc
	v_add_co_u32_e32 v198, vcc, s23, v34
	v_lshl_add_u64 v[28:29], v[26:27], 0, v[68:69]
	s_nop 0
	v_addc_co_u32_e32 v199, vcc, 0, v35, vcc
	v_add_co_u32_e32 v154, vcc, s40, v34
	v_lshl_add_u64 v[30:31], v[26:27], 0, v[70:71]
	s_nop 0
	v_addc_co_u32_e32 v155, vcc, 0, v35, vcc
	v_add_co_u32_e32 v158, vcc, s41, v34
	global_load_dwordx4 v[2:5], v[2:3], off nt
	s_nop 0
	global_load_dwordx4 v[6:9], v[6:7], off nt
	v_addc_co_u32_e32 v159, vcc, 0, v35, vcc
	v_add_co_u32_e32 v162, vcc, s42, v34
	global_load_dwordx4 v[10:13], v[10:11], off nt
	s_nop 0
	global_load_dwordx4 v[14:17], v[14:15], off nt
	v_addc_co_u32_e32 v163, vcc, 0, v35, vcc
	v_add_co_u32_e32 v166, vcc, s43, v34
	global_load_dwordx4 v[18:21], v[18:19], off nt
	s_nop 0
	global_load_dwordx4 v[22:25], v[22:23], off nt
	v_addc_co_u32_e32 v167, vcc, 0, v35, vcc
	v_add_co_u32_e32 v74, vcc, s44, v34
	global_load_dwordx4 v[26:29], v[28:29], off nt
	s_nop 0
	global_load_dwordx4 v[30:33], v[30:31], off nt
	v_addc_co_u32_e32 v75, vcc, 0, v35, vcc
	v_add_co_u32_e32 v78, vcc, s45, v34
	v_lshl_or_b32 v50, v66, 13, s62
	s_nop 0
	v_addc_co_u32_e32 v79, vcc, 0, v35, vcc
	v_add_co_u32_e32 v82, vcc, s46, v34
	s_nop 1
	v_addc_co_u32_e32 v83, vcc, 0, v35, vcc
	v_add_co_u32_e32 v86, vcc, s47, v34
	s_nop 1
	v_addc_co_u32_e32 v87, vcc, 0, v35, vcc
	v_add_co_u32_e32 v90, vcc, s48, v34
	global_load_dword v72, v[74:75], off offset:-4096 nt
	s_nop 0
	global_load_dword v74, v[74:75], off nt
	s_nop 0
	global_load_dword v76, v[78:79], off offset:-4096 nt
	s_nop 0
	global_load_dword v78, v[78:79], off nt
	s_nop 0
	global_load_dword v80, v[82:83], off offset:-4096 nt
	s_nop 0
	global_load_dword v82, v[82:83], off nt
	s_nop 0
	global_load_dword v84, v[86:87], off offset:-4096 nt
	s_nop 0
	global_load_dword v86, v[86:87], off nt
	v_addc_co_u32_e32 v91, vcc, 0, v35, vcc
	v_add_co_u32_e32 v94, vcc, s49, v34
	s_waitcnt vmcnt(7)
	v_mov_b32_e32 v73, v72
	v_addc_co_u32_e32 v95, vcc, 0, v35, vcc
	v_add_co_u32_e32 v98, vcc, s50, v34
	s_waitcnt vmcnt(6)
	v_mov_b32_e32 v75, v74
	v_addc_co_u32_e32 v99, vcc, 0, v35, vcc
	v_add_co_u32_e32 v102, vcc, s51, v34
	s_waitcnt vmcnt(5)
	v_mov_b32_e32 v77, v76
	v_addc_co_u32_e32 v103, vcc, 0, v35, vcc
	v_add_co_u32_e32 v106, vcc, s52, v34
	global_load_dword v88, v[90:91], off offset:-4096 nt
	s_nop 0
	global_load_dword v90, v[90:91], off nt
	s_nop 0
	global_load_dword v92, v[94:95], off offset:-4096 nt
	s_nop 0
	global_load_dword v94, v[94:95], off nt
	s_nop 0
	global_load_dword v96, v[98:99], off offset:-4096 nt
	s_nop 0
	global_load_dword v98, v[98:99], off nt
	s_nop 0
	global_load_dword v100, v[102:103], off offset:-4096 nt
	s_nop 0
	global_load_dword v102, v[102:103], off nt
	v_addc_co_u32_e32 v107, vcc, 0, v35, vcc
	v_add_co_u32_e32 v110, vcc, s53, v34
	s_waitcnt vmcnt(12)
	v_mov_b32_e32 v79, v78
	v_addc_co_u32_e32 v111, vcc, 0, v35, vcc
	v_add_co_u32_e32 v114, vcc, s54, v34
	s_waitcnt vmcnt(11)
	v_mov_b32_e32 v81, v80
	v_addc_co_u32_e32 v115, vcc, 0, v35, vcc
	v_add_co_u32_e32 v118, vcc, s55, v34
	s_waitcnt vmcnt(10)
	v_mov_b32_e32 v83, v82
	v_addc_co_u32_e32 v119, vcc, 0, v35, vcc
	v_add_co_u32_e32 v122, vcc, s56, v34
	s_waitcnt vmcnt(9)
	v_mov_b32_e32 v85, v84
	v_addc_co_u32_e32 v123, vcc, 0, v35, vcc
	v_add_co_u32_e32 v126, vcc, s57, v34
	s_waitcnt vmcnt(8)
	v_mov_b32_e32 v87, v86
	v_addc_co_u32_e32 v127, vcc, 0, v35, vcc
	v_add_co_u32_e32 v130, vcc, s58, v34
	s_waitcnt vmcnt(7)
	v_mov_b32_e32 v89, v88
	v_addc_co_u32_e32 v131, vcc, 0, v35, vcc
	v_add_co_u32_e32 v134, vcc, s59, v34
	s_waitcnt vmcnt(6)
	v_mov_b32_e32 v91, v90
	v_addc_co_u32_e32 v135, vcc, 0, v35, vcc
	v_add_co_u32_e32 v150, vcc, s60, v34
	s_waitcnt vmcnt(5)
	v_mov_b32_e32 v93, v92
	v_addc_co_u32_e32 v151, vcc, 0, v35, vcc
	global_load_dword v104, v[106:107], off offset:-4096 nt
	s_nop 0
	global_load_dword v106, v[106:107], off nt
	s_nop 0
	global_load_dword v108, v[110:111], off offset:-4096 nt
	s_nop 0
	global_load_dword v110, v[110:111], off nt
	s_nop 0
	global_load_dword v112, v[114:115], off offset:-4096 nt
	s_nop 0
	global_load_dword v114, v[114:115], off nt
	s_nop 0
	global_load_dword v116, v[118:119], off offset:-4096 nt
	s_nop 0
	global_load_dword v118, v[118:119], off nt
	s_nop 0
	global_load_dword v120, v[122:123], off offset:-4096 nt
	s_nop 0
	global_load_dword v122, v[122:123], off nt
	s_nop 0
	global_load_dword v124, v[126:127], off offset:-4096 nt
	s_nop 0
	global_load_dword v126, v[126:127], off nt
	s_nop 0
	global_load_dword v128, v[130:131], off offset:-4096 nt
	s_nop 0
	global_load_dword v130, v[130:131], off nt
	s_nop 0
	global_load_dword v132, v[134:135], off offset:-4096 nt
	s_nop 0
	global_load_dword v134, v[134:135], off nt
	s_nop 0
	global_load_dword v136, v36, s[4:5] nt
	global_load_dword v138, v[38:39], off offset:-4096 nt
	global_load_dword v140, v[38:39], off nt
	global_load_dword v142, v[40:41], off offset:-4096 nt
	global_load_dword v144, v[40:41], off nt
	global_load_dword v146, v[42:43], off offset:-4096 nt
	global_load_dword v148, v[42:43], off nt
	s_nop 0
	global_load_dword v150, v[150:151], off nt
	s_nop 0
	global_load_dword v152, v[154:155], off offset:-4096 nt
	s_nop 0
	global_load_dword v154, v[154:155], off nt
	s_nop 0
	global_load_dword v156, v[158:159], off offset:-4096 nt
	s_nop 0
	global_load_dword v158, v[158:159], off nt
	s_nop 0
	global_load_dword v160, v[162:163], off offset:-4096 nt
	s_nop 0
	global_load_dword v162, v[162:163], off nt
	s_nop 0
	global_load_dword v164, v[166:167], off offset:-4096 nt
	s_nop 0
	global_load_dword v166, v[166:167], off nt
	v_add_co_u32_e32 v36, vcc, s39, v34
	s_lshl_b32 s4, s33, 8
	s_nop 0
	v_addc_co_u32_e32 v37, vcc, 0, v35, vcc
	global_load_dword v168, v[36:37], off offset:-4096 nt
	global_load_dword v170, v[36:37], off nt
	global_load_dword v172, v[198:199], off nt
	v_add_co_u32_e32 v36, vcc, s20, v34
	s_ashr_i32 s5, s4, 31
	s_nop 0
	v_addc_co_u32_e32 v37, vcc, 0, v35, vcc
	v_add_co_u32_e32 v38, vcc, s21, v34
	s_lshl_b64 s[4:5], s[4:5], 1
	s_nop 0
	v_addc_co_u32_e32 v39, vcc, 0, v35, vcc
	v_add_co_u32_e32 v34, vcc, s22, v34
	s_add_u32 s26, s8, s4
	s_nop 0
	v_addc_co_u32_e32 v35, vcc, 0, v35, vcc
	global_load_dword v174, v[44:45], off offset:-4096 nt
	global_load_dword v176, v[44:45], off nt
	global_load_dword v178, v[46:47], off offset:-4096 nt
	global_load_dword v180, v[46:47], off nt
	global_load_dword v182, v[48:49], off offset:-4096 nt
	global_load_dword v184, v[48:49], off nt
	global_load_dword v186, v[36:37], off offset:-4096 nt
	global_load_dword v188, v[36:37], off nt
	global_load_dword v190, v[38:39], off offset:-4096 nt
	global_load_dword v192, v[38:39], off nt
	global_load_dword v194, v[34:35], off offset:-4096 nt
	global_load_dword v196, v[34:35], off nt
	s_nop 0
	global_load_dword v198, v[198:199], off offset:-4096 nt
	ds_write_b128 v1, v[2:5]
	ds_write_b128 v67, v[6:9]
	ds_write_b128 v209, v[10:13]
	ds_write_b128 v211, v[14:17]
	ds_write_b128 v212, v[18:21]
	ds_write_b128 v213, v[22:25]
	ds_write_b128 v214, v[26:29]
	ds_write_b128 v215, v[30:33]
	s_waitcnt lgkmcnt(0)
	s_addc_u32 s27, s9, s5
	s_waitcnt vmcnt(52)
	v_mov_b32_e32 v95, v94
	s_waitcnt vmcnt(51)
	v_mov_b32_e32 v97, v96
	s_waitcnt vmcnt(50)
	v_mov_b32_e32 v99, v98
	s_waitcnt vmcnt(49)
	v_mov_b32_e32 v101, v100
	s_waitcnt vmcnt(48)
	v_mov_b32_e32 v103, v102
	s_mov_b32 s4, 0
	v_lshl_add_u64 v[200:201], s[26:27], 0, v[50:51]
	s_waitcnt vmcnt(47)
	v_mov_b32_e32 v105, v104
	s_waitcnt vmcnt(46)
	v_mov_b32_e32 v107, v106
	s_waitcnt vmcnt(45)
	v_mov_b32_e32 v109, v108
	s_waitcnt vmcnt(44)
	v_mov_b32_e32 v111, v110
	s_waitcnt vmcnt(43)
	v_mov_b32_e32 v113, v112
	s_waitcnt vmcnt(42)
	v_mov_b32_e32 v115, v114
	s_waitcnt vmcnt(41)
	v_mov_b32_e32 v117, v116
	s_waitcnt vmcnt(40)
	v_mov_b32_e32 v119, v118
	s_waitcnt vmcnt(39)
	v_mov_b32_e32 v121, v120
	s_waitcnt vmcnt(38)
	v_mov_b32_e32 v123, v122
	s_waitcnt vmcnt(37)
	v_mov_b32_e32 v125, v124
	s_waitcnt vmcnt(36)
	v_mov_b32_e32 v127, v126
	s_waitcnt vmcnt(35)
	v_mov_b32_e32 v129, v128
	s_waitcnt vmcnt(34)
	v_mov_b32_e32 v131, v130
	s_waitcnt vmcnt(33)
	v_mov_b32_e32 v133, v132
	s_waitcnt vmcnt(32)
	v_mov_b32_e32 v135, v134
	s_waitcnt vmcnt(31)
	v_mov_b32_e32 v137, v136
	s_waitcnt vmcnt(30)
	v_mov_b32_e32 v139, v138
	s_waitcnt vmcnt(29)
	v_mov_b32_e32 v141, v140
	s_waitcnt vmcnt(28)
	v_mov_b32_e32 v143, v142
	s_waitcnt vmcnt(27)
	v_mov_b32_e32 v145, v144
	s_waitcnt vmcnt(26)
	v_mov_b32_e32 v147, v146
	s_waitcnt vmcnt(25)
	v_mov_b32_e32 v149, v148
	s_waitcnt vmcnt(24)
	v_mov_b32_e32 v151, v150
	s_waitcnt vmcnt(23)
	v_mov_b32_e32 v153, v152
	s_waitcnt vmcnt(22)
	v_mov_b32_e32 v155, v154
	s_waitcnt vmcnt(21)
	v_mov_b32_e32 v157, v156
	s_waitcnt vmcnt(20)
	v_mov_b32_e32 v159, v158
	s_waitcnt vmcnt(19)
	v_mov_b32_e32 v161, v160
	s_waitcnt vmcnt(18)
	v_mov_b32_e32 v163, v162
	s_waitcnt vmcnt(17)
	v_mov_b32_e32 v165, v164
	s_waitcnt vmcnt(16)
	v_mov_b32_e32 v167, v166
	s_waitcnt vmcnt(15)
	v_mov_b32_e32 v169, v168
	s_waitcnt vmcnt(14)
	v_mov_b32_e32 v171, v170
	s_waitcnt vmcnt(13)
	v_mov_b32_e32 v173, v172
	s_waitcnt vmcnt(12)
	v_mov_b32_e32 v175, v174
	s_waitcnt vmcnt(11)
	v_mov_b32_e32 v177, v176
	s_waitcnt vmcnt(10)
	v_mov_b32_e32 v179, v178
	s_waitcnt vmcnt(9)
	v_mov_b32_e32 v181, v180
	s_waitcnt vmcnt(8)
	v_mov_b32_e32 v183, v182
	s_waitcnt vmcnt(7)
	v_mov_b32_e32 v185, v184
	s_waitcnt vmcnt(6)
	v_mov_b32_e32 v187, v186
	s_waitcnt vmcnt(5)
	v_mov_b32_e32 v189, v188
	s_waitcnt vmcnt(4)
	v_mov_b32_e32 v191, v190
	s_waitcnt vmcnt(3)
	v_mov_b32_e32 v193, v192
	s_waitcnt vmcnt(2)
	v_mov_b32_e32 v195, v194
	s_waitcnt vmcnt(1)
	v_mov_b32_e32 v197, v196
	s_waitcnt vmcnt(0)
	v_mov_b32_e32 v199, v198

.LBB0_180:
	s_mul_hi_i32 s12, s3, 0xa57eb503
	s_add_i32 s12, s12, s3
	s_lshr_b32 s13, s12, 31
	s_ashr_i32 s14, s12, 7
	s_add_i32 s14, s14, s13
	s_mul_i32 s12, s14, 0xc6
	s_sub_i32 s12, s3, s12
	s_mul_i32 s13, s12, 0x7c2
	s_lshr_b32 s15, s13, 31
	s_lshr_b32 s13, s13, 16
	s_add_i32 s13, s13, s15
	s_sext_i32_i16 s15, s13
	v_lshl_or_b32 v2, s15, 6, v66
	v_ashrrev_i32_e32 v3, 31, v2
	s_waitcnt lgkmcnt(0)
	v_lshl_add_u64 v[4:5], v[2:3], 2, s[4:5]
	global_load_dword v68, v[4:5], off nt
	s_mul_i32 s13, s13, 33
	s_sub_i32 s15, s12, s13
	v_mul_hi_i32_i24_e32 v5, 0x1800, v2
	v_mul_i32_i24_e32 v4, 0x1800, v2
	s_mul_i32 s12, s14, 0x60
	v_lshl_add_u64 v[4:5], s[6:7], 0, v[4:5]
	s_ashr_i32 s13, s12, 31
	s_sext_i32_i16 s15, s15
	v_lshl_add_u64 v[50:51], s[12:13], 2, v[4:5]
	s_mov_b64 s[12:13], -1
	s_cmp_lt_i32 s15, 32
	s_mul_i32 s20, s14, 0x120
	v_lshl_add_u64 v[70:71], v[2:3], 1, s[10:11]
	s_cbranch_scc1 .LBB0_184
	s_add_i32 s17, s20, 0x100
	global_load_dwordx4 v[14:17], v[50:51], off offset:256 nt
	global_load_dwordx4 v[18:21], v[50:51], off offset:272 nt
	global_load_dwordx4 v[22:25], v[50:51], off offset:288 nt
	global_load_dwordx4 v[26:29], v[50:51], off offset:304 nt
	global_load_dwordx4 v[30:33], v[50:51], off offset:320 nt
	global_load_dwordx4 v[34:37], v[50:51], off offset:336 nt
	global_load_dwordx4 v[38:41], v[50:51], off offset:352 nt
	global_load_dwordx4 v[42:45], v[50:51], off offset:368 nt
	s_waitcnt vmcnt(0)
	v_mov_b32_e32 v69, v68
	s_add_i32 s33, s17, 0
	s_add_i32 s27, s17, 1
	s_add_i32 s42, s17, 2
	s_add_i32 s39, s17, 3
	v_pk_mul_f32 v[2:3], v[68:69], v[14:15]
	v_pk_mul_f32 v[4:5], v[68:69], v[16:17]
	v_mad_i64_i32 v[6:7], s[40:41], s33, v1, v[70:71]
	v_mad_i64_i32 v[8:9], s[40:41], s27, v1, v[70:71]
	v_mad_i64_i32 v[10:11], s[40:41], s42, v1, v[70:71]
	v_mad_i64_i32 v[12:13], s[40:41], s39, v1, v[70:71]
	v_cvt_pk_bf16_f32 v2, v2, v3
	v_cvt_pk_bf16_f32 v3, v4, v5
	global_store_short v[6:7], v2, off
	global_store_short_d16_hi v[8:9], v2, off
	global_store_short v[10:11], v3, off
	global_store_short_d16_hi v[12:13], v3, off
	s_add_i32 s33, s17, 4
	s_add_i32 s27, s17, 5
	s_add_i32 s42, s17, 6
	s_add_i32 s39, s17, 7
	v_pk_mul_f32 v[2:3], v[68:69], v[18:19]
	v_pk_mul_f32 v[4:5], v[68:69], v[20:21]
	v_mad_i64_i32 v[6:7], s[40:41], s33, v1, v[70:71]
	v_mad_i64_i32 v[8:9], s[40:41], s27, v1, v[70:71]
	v_mad_i64_i32 v[10:11], s[40:41], s42, v1, v[70:71]
	v_mad_i64_i32 v[12:13], s[40:41], s39, v1, v[70:71]
	v_cvt_pk_bf16_f32 v2, v2, v3
	v_cvt_pk_bf16_f32 v3, v4, v5
	global_store_short v[6:7], v2, off
	global_store_short_d16_hi v[8:9], v2, off
	global_store_short v[10:11], v3, off
	global_store_short_d16_hi v[12:13], v3, off
	s_add_i32 s33, s17, 8
	s_add_i32 s27, s17, 9
	s_add_i32 s42, s17, 10
	s_add_i32 s39, s17, 11
	v_pk_mul_f32 v[2:3], v[68:69], v[22:23]
	v_pk_mul_f32 v[4:5], v[68:69], v[24:25]
	v_mad_i64_i32 v[6:7], s[40:41], s33, v1, v[70:71]
	v_mad_i64_i32 v[8:9], s[40:41], s27, v1, v[70:71]
	v_mad_i64_i32 v[10:11], s[40:41], s42, v1, v[70:71]
	v_mad_i64_i32 v[12:13], s[40:41], s39, v1, v[70:71]
	v_cvt_pk_bf16_f32 v2, v2, v3
	v_cvt_pk_bf16_f32 v3, v4, v5
	global_store_short v[6:7], v2, off
	global_store_short_d16_hi v[8:9], v2, off
	global_store_short v[10:11], v3, off
	global_store_short_d16_hi v[12:13], v3, off
	s_add_i32 s33, s17, 12
	s_add_i32 s27, s17, 13
	s_add_i32 s42, s17, 14
	s_add_i32 s39, s17, 15
	v_pk_mul_f32 v[2:3], v[68:69], v[26:27]
	v_pk_mul_f32 v[4:5], v[68:69], v[28:29]
	v_mad_i64_i32 v[6:7], s[40:41], s33, v1, v[70:71]
	v_mad_i64_i32 v[8:9], s[40:41], s27, v1, v[70:71]
	v_mad_i64_i32 v[10:11], s[40:41], s42, v1, v[70:71]
	v_mad_i64_i32 v[12:13], s[40:41], s39, v1, v[70:71]
	v_cvt_pk_bf16_f32 v2, v2, v3
	v_cvt_pk_bf16_f32 v3, v4, v5
	global_store_short v[6:7], v2, off
	global_store_short_d16_hi v[8:9], v2, off
	global_store_short v[10:11], v3, off
	global_store_short_d16_hi v[12:13], v3, off
	s_add_i32 s33, s17, 16
	s_add_i32 s27, s17, 17
	s_add_i32 s42, s17, 18
	s_add_i32 s39, s17, 19
	v_pk_mul_f32 v[2:3], v[68:69], v[30:31]
	v_pk_mul_f32 v[4:5], v[68:69], v[32:33]
	v_mad_i64_i32 v[6:7], s[40:41], s33, v1, v[70:71]
	v_mad_i64_i32 v[8:9], s[40:41], s27, v1, v[70:71]
	v_mad_i64_i32 v[10:11], s[40:41], s42, v1, v[70:71]
	v_mad_i64_i32 v[12:13], s[40:41], s39, v1, v[70:71]
	v_cvt_pk_bf16_f32 v2, v2, v3
	v_cvt_pk_bf16_f32 v3, v4, v5
	global_store_short v[6:7], v2, off
	global_store_short_d16_hi v[8:9], v2, off
	global_store_short v[10:11], v3, off
	global_store_short_d16_hi v[12:13], v3, off
	s_add_i32 s33, s17, 20
	s_add_i32 s27, s17, 21
	s_add_i32 s42, s17, 22
	s_add_i32 s39, s17, 23
	v_pk_mul_f32 v[2:3], v[68:69], v[34:35]
	v_pk_mul_f32 v[4:5], v[68:69], v[36:37]
	v_mad_i64_i32 v[6:7], s[40:41], s33, v1, v[70:71]
	v_mad_i64_i32 v[8:9], s[40:41], s27, v1, v[70:71]
	v_mad_i64_i32 v[10:11], s[40:41], s42, v1, v[70:71]
	v_mad_i64_i32 v[12:13], s[40:41], s39, v1, v[70:71]
	v_cvt_pk_bf16_f32 v2, v2, v3
	v_cvt_pk_bf16_f32 v3, v4, v5
	global_store_short v[6:7], v2, off
	global_store_short_d16_hi v[8:9], v2, off
	global_store_short v[10:11], v3, off
	global_store_short_d16_hi v[12:13], v3, off
	s_add_i32 s33, s17, 24
	s_add_i32 s27, s17, 25
	s_add_i32 s42, s17, 26
	s_add_i32 s39, s17, 27
	v_pk_mul_f32 v[2:3], v[68:69], v[38:39]
	v_pk_mul_f32 v[4:5], v[68:69], v[40:41]
	v_mad_i64_i32 v[6:7], s[40:41], s33, v1, v[70:71]
	v_mad_i64_i32 v[8:9], s[40:41], s27, v1, v[70:71]
	v_mad_i64_i32 v[10:11], s[40:41], s42, v1, v[70:71]
	v_mad_i64_i32 v[12:13], s[40:41], s39, v1, v[70:71]
	v_cvt_pk_bf16_f32 v2, v2, v3
	v_cvt_pk_bf16_f32 v3, v4, v5
	global_store_short v[6:7], v2, off
	global_store_short_d16_hi v[8:9], v2, off
	global_store_short v[10:11], v3, off
	global_store_short_d16_hi v[12:13], v3, off
	s_add_i32 s33, s17, 28
	s_add_i32 s27, s17, 29
	s_add_i32 s42, s17, 30
	s_add_i32 s39, s17, 31
	v_pk_mul_f32 v[2:3], v[68:69], v[42:43]
	v_pk_mul_f32 v[4:5], v[68:69], v[44:45]
	v_mad_i64_i32 v[6:7], s[40:41], s33, v1, v[70:71]
	v_mad_i64_i32 v[8:9], s[40:41], s27, v1, v[70:71]
	v_mad_i64_i32 v[10:11], s[40:41], s42, v1, v[70:71]
	v_mad_i64_i32 v[12:13], s[40:41], s39, v1, v[70:71]
	v_cvt_pk_bf16_f32 v2, v2, v3
	v_cvt_pk_bf16_f32 v3, v4, v5
	global_store_short v[6:7], v2, off
	global_store_short_d16_hi v[8:9], v2, off
	global_store_short v[10:11], v3, off
	global_store_short_d16_hi v[12:13], v3, off
	s_branch .LBB0_179
.LBB0_184:
	s_and_b64 vcc, exec, s[12:13]
	s_cbranch_vccz .LBB0_179
	s_lshl_b32 s14, s14, 6
	s_lshl_b32 s12, s15, 3
	s_ashr_i32 s15, s14, 31
	s_lshl_b64 s[14:15], s[14:15], 2
	s_add_u32 s21, s8, s14
	s_addc_u32 s22, s9, s15
	s_ashr_i32 s13, s12, 31
	s_lshl_b64 s[14:15], s[12:13], 12
	s_add_u32 s14, s21, s14
	s_addc_u32 s15, s22, s15
	global_load_dwordx4 v[72:75], v67, s[14:15] nt
	global_load_dwordx4 v[14:17], v[50:51], off nt
	global_load_dwordx4 v[10:13], v[50:51], off offset:16 nt
	global_load_dwordx4 v[76:79], v67, s[14:15] offset:16 nt
	global_load_dwordx4 v[80:83], v67, s[14:15] offset:32 nt
	global_load_dwordx4 v[6:9], v[50:51], off offset:32 nt
	global_load_dwordx4 v[2:5], v[50:51], off offset:48 nt
	global_load_dwordx4 v[84:87], v67, s[14:15] offset:48 nt
	global_load_dwordx4 v[88:91], v67, s[14:15] offset:64 nt
	global_load_dwordx4 v[30:33], v[50:51], off offset:64 nt
	global_load_dwordx4 v[26:29], v[50:51], off offset:80 nt
	global_load_dwordx4 v[92:95], v67, s[14:15] offset:80 nt
	global_load_dwordx4 v[96:99], v67, s[14:15] offset:96 nt
	global_load_dwordx4 v[22:25], v[50:51], off offset:96 nt
	global_load_dwordx4 v[18:21], v[50:51], off offset:112 nt
	global_load_dwordx4 v[100:103], v67, s[14:15] offset:112 nt
	global_load_dwordx4 v[104:107], v67, s[14:15] offset:128 nt
	global_load_dwordx4 v[46:49], v[50:51], off offset:128 nt
	global_load_dwordx4 v[42:45], v[50:51], off offset:144 nt
	global_load_dwordx4 v[108:111], v67, s[14:15] offset:144 nt
	global_load_dwordx4 v[112:115], v67, s[14:15] offset:160 nt
	global_load_dwordx4 v[38:41], v[50:51], off offset:160 nt
	global_load_dwordx4 v[34:37], v[50:51], off offset:176 nt
	global_load_dwordx4 v[116:119], v67, s[14:15] offset:176 nt
	global_load_dwordx4 v[120:123], v67, s[14:15] offset:192 nt
	global_load_dwordx4 v[62:65], v[50:51], off offset:192 nt
	global_load_dwordx4 v[58:61], v[50:51], off offset:208 nt
	global_load_dwordx4 v[124:127], v67, s[14:15] offset:208 nt
	global_load_dwordx4 v[128:131], v67, s[14:15] offset:224 nt
	global_load_dwordx4 v[54:57], v[50:51], off offset:224 nt
	s_nop 0
	global_load_dwordx4 v[50:53], v[50:51], off offset:240 nt
	s_nop 0
	global_load_dwordx4 v[132:135], v67, s[14:15] offset:240 nt
	s_add_i32 s13, s12, s20
	s_or_b32 s14, s12, 1
	v_mad_i64_i32 v[136:137], s[16:17], s13, v1, v[70:71]
	s_ashr_i32 s15, s14, 31
	s_lshl_b64 s[16:17], s[14:15], 12
	s_add_u32 s16, s21, s16
	s_addc_u32 s17, s22, s17
	s_add_i32 s13, s14, s20
	s_or_b32 s14, s12, 2
	s_ashr_i32 s15, s14, 31
	s_waitcnt vmcnt(30)
	v_fma_f32 v69, v14, v72, 0
	v_fmac_f32_e32 v69, v15, v73
	v_fmac_f32_e32 v69, v16, v74
	v_fmac_f32_e32 v69, v17, v75
	s_waitcnt vmcnt(28)
	v_fmac_f32_e32 v69, v10, v76
	v_fmac_f32_e32 v69, v11, v77
	v_fmac_f32_e32 v69, v12, v78
	v_fmac_f32_e32 v69, v13, v79
	s_waitcnt vmcnt(26)
	v_fmac_f32_e32 v69, v6, v80
	v_fmac_f32_e32 v69, v7, v81
	v_fmac_f32_e32 v69, v8, v82
	v_fmac_f32_e32 v69, v9, v83
	s_waitcnt vmcnt(24)
	v_fmac_f32_e32 v69, v2, v84
	v_fmac_f32_e32 v69, v3, v85
	v_fmac_f32_e32 v69, v4, v86
	v_fmac_f32_e32 v69, v5, v87
	s_waitcnt vmcnt(22)
	v_fmac_f32_e32 v69, v30, v88
	v_fmac_f32_e32 v69, v31, v89
	v_fmac_f32_e32 v69, v32, v90
	v_fmac_f32_e32 v69, v33, v91
	s_waitcnt vmcnt(20)
	v_fmac_f32_e32 v69, v26, v92
	v_fmac_f32_e32 v69, v27, v93
	v_fmac_f32_e32 v69, v28, v94
	v_fmac_f32_e32 v69, v29, v95
	s_waitcnt vmcnt(18)
	v_fmac_f32_e32 v69, v22, v96
	v_fmac_f32_e32 v69, v23, v97
	v_fmac_f32_e32 v69, v24, v98
	v_fmac_f32_e32 v69, v25, v99
	s_waitcnt vmcnt(16)
	v_fmac_f32_e32 v69, v18, v100
	v_fmac_f32_e32 v69, v19, v101
	v_fmac_f32_e32 v69, v20, v102
	v_fmac_f32_e32 v69, v21, v103
	s_waitcnt vmcnt(14)
	v_fmac_f32_e32 v69, v46, v104
	v_fmac_f32_e32 v69, v47, v105
	v_fmac_f32_e32 v69, v48, v106
	v_fmac_f32_e32 v69, v49, v107
	s_waitcnt vmcnt(12)
	v_fmac_f32_e32 v69, v42, v108
	v_fmac_f32_e32 v69, v43, v109
	v_fmac_f32_e32 v69, v44, v110
	v_fmac_f32_e32 v69, v45, v111
	s_waitcnt vmcnt(10)
	v_fmac_f32_e32 v69, v38, v112
	v_fmac_f32_e32 v69, v39, v113
	v_fmac_f32_e32 v69, v40, v114
	v_fmac_f32_e32 v69, v41, v115
	s_waitcnt vmcnt(8)
	v_fmac_f32_e32 v69, v34, v116
	v_fmac_f32_e32 v69, v35, v117
	v_fmac_f32_e32 v69, v36, v118
	v_fmac_f32_e32 v69, v37, v119
	s_waitcnt vmcnt(6)
	v_fmac_f32_e32 v69, v62, v120
	v_fmac_f32_e32 v69, v63, v121
	v_fmac_f32_e32 v69, v64, v122
	v_fmac_f32_e32 v69, v65, v123
	s_waitcnt vmcnt(4)
	v_fmac_f32_e32 v69, v58, v124
	v_fmac_f32_e32 v69, v59, v125
	v_fmac_f32_e32 v69, v60, v126
	v_fmac_f32_e32 v69, v61, v127
	s_waitcnt vmcnt(2)
	v_fmac_f32_e32 v69, v54, v128
	v_fmac_f32_e32 v69, v55, v129
	v_fmac_f32_e32 v69, v56, v130
	v_fmac_f32_e32 v69, v57, v131
	s_waitcnt vmcnt(0)
	v_fmac_f32_e32 v69, v50, v132
	v_fmac_f32_e32 v69, v51, v133
	v_fmac_f32_e32 v69, v52, v134
	v_fmac_f32_e32 v69, v53, v135
	v_mul_f32_e32 v69, v68, v69
	v_cvt_pk_bf16_f32 v69, v69, s0
	global_store_short v[136:137], v69, off
	global_load_dwordx4 v[72:75], v67, s[16:17] nt
	global_load_dwordx4 v[76:79], v67, s[16:17] offset:16 nt
	global_load_dwordx4 v[80:83], v67, s[16:17] offset:32 nt
	global_load_dwordx4 v[84:87], v67, s[16:17] offset:48 nt
	global_load_dwordx4 v[88:91], v67, s[16:17] offset:64 nt
	global_load_dwordx4 v[92:95], v67, s[16:17] offset:80 nt
	global_load_dwordx4 v[96:99], v67, s[16:17] offset:96 nt
	global_load_dwordx4 v[100:103], v67, s[16:17] offset:112 nt
	global_load_dwordx4 v[104:107], v67, s[16:17] offset:128 nt
	global_load_dwordx4 v[108:111], v67, s[16:17] offset:144 nt
	global_load_dwordx4 v[112:115], v67, s[16:17] offset:160 nt
	global_load_dwordx4 v[116:119], v67, s[16:17] offset:176 nt
	global_load_dwordx4 v[120:123], v67, s[16:17] offset:192 nt
	global_load_dwordx4 v[124:127], v67, s[16:17] offset:208 nt
	global_load_dwordx4 v[128:131], v67, s[16:17] offset:224 nt
	global_load_dwordx4 v[132:135], v67, s[16:17] offset:240 nt
	v_mad_i64_i32 v[136:137], s[16:17], s13, v1, v[70:71]
	s_lshl_b64 s[16:17], s[14:15], 12
	s_add_u32 s16, s21, s16
	s_addc_u32 s17, s22, s17
	s_add_i32 s13, s14, s20
	s_or_b32 s14, s12, 3
	s_ashr_i32 s15, s14, 31
	s_waitcnt vmcnt(15)
	v_fma_f32 v69, v14, v72, 0
	v_fmac_f32_e32 v69, v15, v73
	v_fmac_f32_e32 v69, v16, v74
	v_fmac_f32_e32 v69, v17, v75
	s_waitcnt vmcnt(14)
	v_fmac_f32_e32 v69, v10, v76
	v_fmac_f32_e32 v69, v11, v77
	v_fmac_f32_e32 v69, v12, v78
	v_fmac_f32_e32 v69, v13, v79
	s_waitcnt vmcnt(13)
	v_fmac_f32_e32 v69, v6, v80
	v_fmac_f32_e32 v69, v7, v81
	v_fmac_f32_e32 v69, v8, v82
	v_fmac_f32_e32 v69, v9, v83
	s_waitcnt vmcnt(12)
	v_fmac_f32_e32 v69, v2, v84
	v_fmac_f32_e32 v69, v3, v85
	v_fmac_f32_e32 v69, v4, v86
	v_fmac_f32_e32 v69, v5, v87
	s_waitcnt vmcnt(11)
	v_fmac_f32_e32 v69, v30, v88
	v_fmac_f32_e32 v69, v31, v89
	v_fmac_f32_e32 v69, v32, v90
	v_fmac_f32_e32 v69, v33, v91
	s_waitcnt vmcnt(10)
	v_fmac_f32_e32 v69, v26, v92
	v_fmac_f32_e32 v69, v27, v93
	v_fmac_f32_e32 v69, v28, v94
	v_fmac_f32_e32 v69, v29, v95
	s_waitcnt vmcnt(9)
	v_fmac_f32_e32 v69, v22, v96
	v_fmac_f32_e32 v69, v23, v97
	v_fmac_f32_e32 v69, v24, v98
	v_fmac_f32_e32 v69, v25, v99
	s_waitcnt vmcnt(8)
	v_fmac_f32_e32 v69, v18, v100
	v_fmac_f32_e32 v69, v19, v101
	v_fmac_f32_e32 v69, v20, v102
	v_fmac_f32_e32 v69, v21, v103
	s_waitcnt vmcnt(7)
	v_fmac_f32_e32 v69, v46, v104
	v_fmac_f32_e32 v69, v47, v105
	v_fmac_f32_e32 v69, v48, v106
	v_fmac_f32_e32 v69, v49, v107
	s_waitcnt vmcnt(6)
	v_fmac_f32_e32 v69, v42, v108
	v_fmac_f32_e32 v69, v43, v109
	v_fmac_f32_e32 v69, v44, v110
	v_fmac_f32_e32 v69, v45, v111
	s_waitcnt vmcnt(5)
	v_fmac_f32_e32 v69, v38, v112
	v_fmac_f32_e32 v69, v39, v113
	v_fmac_f32_e32 v69, v40, v114
	v_fmac_f32_e32 v69, v41, v115
	s_waitcnt vmcnt(4)
	v_fmac_f32_e32 v69, v34, v116
	v_fmac_f32_e32 v69, v35, v117
	v_fmac_f32_e32 v69, v36, v118
	v_fmac_f32_e32 v69, v37, v119
	s_waitcnt vmcnt(3)
	v_fmac_f32_e32 v69, v62, v120
	v_fmac_f32_e32 v69, v63, v121
	v_fmac_f32_e32 v69, v64, v122
	v_fmac_f32_e32 v69, v65, v123
	s_waitcnt vmcnt(2)
	v_fmac_f32_e32 v69, v58, v124
	v_fmac_f32_e32 v69, v59, v125
	v_fmac_f32_e32 v69, v60, v126
	v_fmac_f32_e32 v69, v61, v127
	s_waitcnt vmcnt(1)
	v_fmac_f32_e32 v69, v54, v128
	v_fmac_f32_e32 v69, v55, v129
	v_fmac_f32_e32 v69, v56, v130
	v_fmac_f32_e32 v69, v57, v131
	s_waitcnt vmcnt(0)
	v_fmac_f32_e32 v69, v50, v132
	v_fmac_f32_e32 v69, v51, v133
	v_fmac_f32_e32 v69, v52, v134
	v_fmac_f32_e32 v69, v53, v135
	v_mul_f32_e32 v69, v68, v69
	v_cvt_pk_bf16_f32 v69, v69, s0
	global_store_short v[136:137], v69, off
	global_load_dwordx4 v[72:75], v67, s[16:17] nt
	global_load_dwordx4 v[76:79], v67, s[16:17] offset:16 nt
	global_load_dwordx4 v[80:83], v67, s[16:17] offset:32 nt
	global_load_dwordx4 v[84:87], v67, s[16:17] offset:48 nt
	global_load_dwordx4 v[88:91], v67, s[16:17] offset:64 nt
	global_load_dwordx4 v[92:95], v67, s[16:17] offset:80 nt
	global_load_dwordx4 v[96:99], v67, s[16:17] offset:96 nt
	global_load_dwordx4 v[100:103], v67, s[16:17] offset:112 nt
	global_load_dwordx4 v[104:107], v67, s[16:17] offset:128 nt
	global_load_dwordx4 v[108:111], v67, s[16:17] offset:144 nt
	global_load_dwordx4 v[112:115], v67, s[16:17] offset:160 nt
	global_load_dwordx4 v[116:119], v67, s[16:17] offset:176 nt
	global_load_dwordx4 v[120:123], v67, s[16:17] offset:192 nt
	global_load_dwordx4 v[124:127], v67, s[16:17] offset:208 nt
	global_load_dwordx4 v[128:131], v67, s[16:17] offset:224 nt
	global_load_dwordx4 v[132:135], v67, s[16:17] offset:240 nt
	v_mad_i64_i32 v[136:137], s[16:17], s13, v1, v[70:71]
	s_lshl_b64 s[16:17], s[14:15], 12
	s_add_u32 s16, s21, s16
	s_addc_u32 s17, s22, s17
	s_add_i32 s13, s14, s20
	s_or_b32 s14, s12, 4
	s_ashr_i32 s15, s14, 31
	s_waitcnt vmcnt(15)
	v_fma_f32 v69, v14, v72, 0
	v_fmac_f32_e32 v69, v15, v73
	v_fmac_f32_e32 v69, v16, v74
	v_fmac_f32_e32 v69, v17, v75
	s_waitcnt vmcnt(14)
	v_fmac_f32_e32 v69, v10, v76
	v_fmac_f32_e32 v69, v11, v77
	v_fmac_f32_e32 v69, v12, v78
	v_fmac_f32_e32 v69, v13, v79
	s_waitcnt vmcnt(13)
	v_fmac_f32_e32 v69, v6, v80
	v_fmac_f32_e32 v69, v7, v81
	v_fmac_f32_e32 v69, v8, v82
	v_fmac_f32_e32 v69, v9, v83
	s_waitcnt vmcnt(12)
	v_fmac_f32_e32 v69, v2, v84
	v_fmac_f32_e32 v69, v3, v85
	v_fmac_f32_e32 v69, v4, v86
	v_fmac_f32_e32 v69, v5, v87
	s_waitcnt vmcnt(11)
	v_fmac_f32_e32 v69, v30, v88
	v_fmac_f32_e32 v69, v31, v89
	v_fmac_f32_e32 v69, v32, v90
	v_fmac_f32_e32 v69, v33, v91
	s_waitcnt vmcnt(10)
	v_fmac_f32_e32 v69, v26, v92
	v_fmac_f32_e32 v69, v27, v93
	v_fmac_f32_e32 v69, v28, v94
	v_fmac_f32_e32 v69, v29, v95
	s_waitcnt vmcnt(9)
	v_fmac_f32_e32 v69, v22, v96
	v_fmac_f32_e32 v69, v23, v97
	v_fmac_f32_e32 v69, v24, v98
	v_fmac_f32_e32 v69, v25, v99
	s_waitcnt vmcnt(8)
	v_fmac_f32_e32 v69, v18, v100
	v_fmac_f32_e32 v69, v19, v101
	v_fmac_f32_e32 v69, v20, v102
	v_fmac_f32_e32 v69, v21, v103
	s_waitcnt vmcnt(7)
	v_fmac_f32_e32 v69, v46, v104
	v_fmac_f32_e32 v69, v47, v105
	v_fmac_f32_e32 v69, v48, v106
	v_fmac_f32_e32 v69, v49, v107
	s_waitcnt vmcnt(6)
	v_fmac_f32_e32 v69, v42, v108
	v_fmac_f32_e32 v69, v43, v109
	v_fmac_f32_e32 v69, v44, v110
	v_fmac_f32_e32 v69, v45, v111
	s_waitcnt vmcnt(5)
	v_fmac_f32_e32 v69, v38, v112
	v_fmac_f32_e32 v69, v39, v113
	v_fmac_f32_e32 v69, v40, v114
	v_fmac_f32_e32 v69, v41, v115
	s_waitcnt vmcnt(4)
	v_fmac_f32_e32 v69, v34, v116
	v_fmac_f32_e32 v69, v35, v117
	v_fmac_f32_e32 v69, v36, v118
	v_fmac_f32_e32 v69, v37, v119
	s_waitcnt vmcnt(3)
	v_fmac_f32_e32 v69, v62, v120
	v_fmac_f32_e32 v69, v63, v121
	v_fmac_f32_e32 v69, v64, v122
	v_fmac_f32_e32 v69, v65, v123
	s_waitcnt vmcnt(2)
	v_fmac_f32_e32 v69, v58, v124
	v_fmac_f32_e32 v69, v59, v125
	v_fmac_f32_e32 v69, v60, v126
	v_fmac_f32_e32 v69, v61, v127
	s_waitcnt vmcnt(1)
	v_fmac_f32_e32 v69, v54, v128
	v_fmac_f32_e32 v69, v55, v129
	v_fmac_f32_e32 v69, v56, v130
	v_fmac_f32_e32 v69, v57, v131
	s_waitcnt vmcnt(0)
	v_fmac_f32_e32 v69, v50, v132
	v_fmac_f32_e32 v69, v51, v133
	v_fmac_f32_e32 v69, v52, v134
	v_fmac_f32_e32 v69, v53, v135
	v_mul_f32_e32 v69, v68, v69
	v_cvt_pk_bf16_f32 v69, v69, s0
	global_store_short v[136:137], v69, off
	global_load_dwordx4 v[72:75], v67, s[16:17] nt
	global_load_dwordx4 v[76:79], v67, s[16:17] offset:16 nt
	global_load_dwordx4 v[80:83], v67, s[16:17] offset:32 nt
	global_load_dwordx4 v[84:87], v67, s[16:17] offset:48 nt
	global_load_dwordx4 v[88:91], v67, s[16:17] offset:64 nt
	global_load_dwordx4 v[92:95], v67, s[16:17] offset:80 nt
	global_load_dwordx4 v[96:99], v67, s[16:17] offset:96 nt
	global_load_dwordx4 v[100:103], v67, s[16:17] offset:112 nt
	global_load_dwordx4 v[104:107], v67, s[16:17] offset:128 nt
	global_load_dwordx4 v[108:111], v67, s[16:17] offset:144 nt
	global_load_dwordx4 v[112:115], v67, s[16:17] offset:160 nt
	global_load_dwordx4 v[116:119], v67, s[16:17] offset:176 nt
	global_load_dwordx4 v[120:123], v67, s[16:17] offset:192 nt
	global_load_dwordx4 v[124:127], v67, s[16:17] offset:208 nt
	global_load_dwordx4 v[128:131], v67, s[16:17] offset:224 nt
	global_load_dwordx4 v[132:135], v67, s[16:17] offset:240 nt
	v_mad_i64_i32 v[136:137], s[16:17], s13, v1, v[70:71]
	s_lshl_b64 s[16:17], s[14:15], 12
	s_add_u32 s16, s21, s16
	s_addc_u32 s17, s22, s17
	s_add_i32 s13, s14, s20
	s_or_b32 s14, s12, 5
	s_ashr_i32 s15, s14, 31
	s_waitcnt vmcnt(15)
	v_fma_f32 v69, v14, v72, 0
	v_fmac_f32_e32 v69, v15, v73
	v_fmac_f32_e32 v69, v16, v74
	v_fmac_f32_e32 v69, v17, v75
	s_waitcnt vmcnt(14)
	v_fmac_f32_e32 v69, v10, v76
	v_fmac_f32_e32 v69, v11, v77
	v_fmac_f32_e32 v69, v12, v78
	v_fmac_f32_e32 v69, v13, v79
	s_waitcnt vmcnt(13)
	v_fmac_f32_e32 v69, v6, v80
	v_fmac_f32_e32 v69, v7, v81
	v_fmac_f32_e32 v69, v8, v82
	v_fmac_f32_e32 v69, v9, v83
	s_waitcnt vmcnt(12)
	v_fmac_f32_e32 v69, v2, v84
	v_fmac_f32_e32 v69, v3, v85
	v_fmac_f32_e32 v69, v4, v86
	v_fmac_f32_e32 v69, v5, v87
	s_waitcnt vmcnt(11)
	v_fmac_f32_e32 v69, v30, v88
	v_fmac_f32_e32 v69, v31, v89
	v_fmac_f32_e32 v69, v32, v90
	v_fmac_f32_e32 v69, v33, v91
	s_waitcnt vmcnt(10)
	v_fmac_f32_e32 v69, v26, v92
	v_fmac_f32_e32 v69, v27, v93
	v_fmac_f32_e32 v69, v28, v94
	v_fmac_f32_e32 v69, v29, v95
	s_waitcnt vmcnt(9)
	v_fmac_f32_e32 v69, v22, v96
	v_fmac_f32_e32 v69, v23, v97
	v_fmac_f32_e32 v69, v24, v98
	v_fmac_f32_e32 v69, v25, v99
	s_waitcnt vmcnt(8)
	v_fmac_f32_e32 v69, v18, v100
	v_fmac_f32_e32 v69, v19, v101
	v_fmac_f32_e32 v69, v20, v102
	v_fmac_f32_e32 v69, v21, v103
	s_waitcnt vmcnt(7)
	v_fmac_f32_e32 v69, v46, v104
	v_fmac_f32_e32 v69, v47, v105
	v_fmac_f32_e32 v69, v48, v106
	v_fmac_f32_e32 v69, v49, v107
	s_waitcnt vmcnt(6)
	v_fmac_f32_e32 v69, v42, v108
	v_fmac_f32_e32 v69, v43, v109
	v_fmac_f32_e32 v69, v44, v110
	v_fmac_f32_e32 v69, v45, v111
	s_waitcnt vmcnt(5)
	v_fmac_f32_e32 v69, v38, v112
	v_fmac_f32_e32 v69, v39, v113
	v_fmac_f32_e32 v69, v40, v114
	v_fmac_f32_e32 v69, v41, v115
	s_waitcnt vmcnt(4)
	v_fmac_f32_e32 v69, v34, v116
	v_fmac_f32_e32 v69, v35, v117
	v_fmac_f32_e32 v69, v36, v118
	v_fmac_f32_e32 v69, v37, v119
	s_waitcnt vmcnt(3)
	v_fmac_f32_e32 v69, v62, v120
	v_fmac_f32_e32 v69, v63, v121
	v_fmac_f32_e32 v69, v64, v122
	v_fmac_f32_e32 v69, v65, v123
	s_waitcnt vmcnt(2)
	v_fmac_f32_e32 v69, v58, v124
	v_fmac_f32_e32 v69, v59, v125
	v_fmac_f32_e32 v69, v60, v126
	v_fmac_f32_e32 v69, v61, v127
	s_waitcnt vmcnt(1)
	v_fmac_f32_e32 v69, v54, v128
	v_fmac_f32_e32 v69, v55, v129
	v_fmac_f32_e32 v69, v56, v130
	v_fmac_f32_e32 v69, v57, v131
	s_waitcnt vmcnt(0)
	v_fmac_f32_e32 v69, v50, v132
	v_fmac_f32_e32 v69, v51, v133
	v_fmac_f32_e32 v69, v52, v134
	v_fmac_f32_e32 v69, v53, v135
	v_mul_f32_e32 v69, v68, v69
	v_cvt_pk_bf16_f32 v69, v69, s0
	global_store_short v[136:137], v69, off
	global_load_dwordx4 v[72:75], v67, s[16:17] nt
	global_load_dwordx4 v[76:79], v67, s[16:17] offset:16 nt
	global_load_dwordx4 v[80:83], v67, s[16:17] offset:32 nt
	global_load_dwordx4 v[84:87], v67, s[16:17] offset:48 nt
	global_load_dwordx4 v[88:91], v67, s[16:17] offset:64 nt
	global_load_dwordx4 v[92:95], v67, s[16:17] offset:80 nt
	global_load_dwordx4 v[96:99], v67, s[16:17] offset:96 nt
	global_load_dwordx4 v[100:103], v67, s[16:17] offset:112 nt
	global_load_dwordx4 v[104:107], v67, s[16:17] offset:128 nt
	global_load_dwordx4 v[108:111], v67, s[16:17] offset:144 nt
	global_load_dwordx4 v[112:115], v67, s[16:17] offset:160 nt
	global_load_dwordx4 v[116:119], v67, s[16:17] offset:176 nt
	global_load_dwordx4 v[120:123], v67, s[16:17] offset:192 nt
	global_load_dwordx4 v[124:127], v67, s[16:17] offset:208 nt
	global_load_dwordx4 v[128:131], v67, s[16:17] offset:224 nt
	global_load_dwordx4 v[132:135], v67, s[16:17] offset:240 nt
	v_mad_i64_i32 v[136:137], s[16:17], s13, v1, v[70:71]
	s_lshl_b64 s[16:17], s[14:15], 12
	s_add_u32 s16, s21, s16
	s_addc_u32 s17, s22, s17
	s_add_i32 s13, s14, s20
	s_or_b32 s14, s12, 6
	s_ashr_i32 s15, s14, 31
	s_waitcnt vmcnt(15)
	v_fma_f32 v69, v14, v72, 0
	v_fmac_f32_e32 v69, v15, v73
	v_fmac_f32_e32 v69, v16, v74
	v_fmac_f32_e32 v69, v17, v75
	s_waitcnt vmcnt(14)
	v_fmac_f32_e32 v69, v10, v76
	v_fmac_f32_e32 v69, v11, v77
	v_fmac_f32_e32 v69, v12, v78
	v_fmac_f32_e32 v69, v13, v79
	s_waitcnt vmcnt(13)
	v_fmac_f32_e32 v69, v6, v80
	v_fmac_f32_e32 v69, v7, v81
	v_fmac_f32_e32 v69, v8, v82
	v_fmac_f32_e32 v69, v9, v83
	s_waitcnt vmcnt(12)
	v_fmac_f32_e32 v69, v2, v84
	v_fmac_f32_e32 v69, v3, v85
	v_fmac_f32_e32 v69, v4, v86
	v_fmac_f32_e32 v69, v5, v87
	s_waitcnt vmcnt(11)
	v_fmac_f32_e32 v69, v30, v88
	v_fmac_f32_e32 v69, v31, v89
	v_fmac_f32_e32 v69, v32, v90
	v_fmac_f32_e32 v69, v33, v91
	s_waitcnt vmcnt(10)
	v_fmac_f32_e32 v69, v26, v92
	v_fmac_f32_e32 v69, v27, v93
	v_fmac_f32_e32 v69, v28, v94
	v_fmac_f32_e32 v69, v29, v95
	s_waitcnt vmcnt(9)
	v_fmac_f32_e32 v69, v22, v96
	v_fmac_f32_e32 v69, v23, v97
	v_fmac_f32_e32 v69, v24, v98
	v_fmac_f32_e32 v69, v25, v99
	s_waitcnt vmcnt(8)
	v_fmac_f32_e32 v69, v18, v100
	v_fmac_f32_e32 v69, v19, v101
	v_fmac_f32_e32 v69, v20, v102
	v_fmac_f32_e32 v69, v21, v103
	s_waitcnt vmcnt(7)
	v_fmac_f32_e32 v69, v46, v104
	v_fmac_f32_e32 v69, v47, v105
	v_fmac_f32_e32 v69, v48, v106
	v_fmac_f32_e32 v69, v49, v107
	s_waitcnt vmcnt(6)
	v_fmac_f32_e32 v69, v42, v108
	v_fmac_f32_e32 v69, v43, v109
	v_fmac_f32_e32 v69, v44, v110
	v_fmac_f32_e32 v69, v45, v111
	s_waitcnt vmcnt(5)
	v_fmac_f32_e32 v69, v38, v112
	v_fmac_f32_e32 v69, v39, v113
	v_fmac_f32_e32 v69, v40, v114
	v_fmac_f32_e32 v69, v41, v115
	s_waitcnt vmcnt(4)
	v_fmac_f32_e32 v69, v34, v116
	v_fmac_f32_e32 v69, v35, v117
	v_fmac_f32_e32 v69, v36, v118
	v_fmac_f32_e32 v69, v37, v119
	s_waitcnt vmcnt(3)
	v_fmac_f32_e32 v69, v62, v120
	v_fmac_f32_e32 v69, v63, v121
	v_fmac_f32_e32 v69, v64, v122
	v_fmac_f32_e32 v69, v65, v123
	s_waitcnt vmcnt(2)
	v_fmac_f32_e32 v69, v58, v124
	v_fmac_f32_e32 v69, v59, v125
	v_fmac_f32_e32 v69, v60, v126
	v_fmac_f32_e32 v69, v61, v127
	s_waitcnt vmcnt(1)
	v_fmac_f32_e32 v69, v54, v128
	v_fmac_f32_e32 v69, v55, v129
	v_fmac_f32_e32 v69, v56, v130
	v_fmac_f32_e32 v69, v57, v131
	s_waitcnt vmcnt(0)
	v_fmac_f32_e32 v69, v50, v132
	v_fmac_f32_e32 v69, v51, v133
	v_fmac_f32_e32 v69, v52, v134
	v_fmac_f32_e32 v69, v53, v135
	v_mul_f32_e32 v69, v68, v69
	v_cvt_pk_bf16_f32 v69, v69, s0
	global_store_short v[136:137], v69, off
	global_load_dwordx4 v[72:75], v67, s[16:17] nt
	global_load_dwordx4 v[76:79], v67, s[16:17] offset:16 nt
	global_load_dwordx4 v[80:83], v67, s[16:17] offset:32 nt
	global_load_dwordx4 v[84:87], v67, s[16:17] offset:48 nt
	global_load_dwordx4 v[88:91], v67, s[16:17] offset:64 nt
	global_load_dwordx4 v[92:95], v67, s[16:17] offset:80 nt
	global_load_dwordx4 v[96:99], v67, s[16:17] offset:96 nt
	global_load_dwordx4 v[100:103], v67, s[16:17] offset:112 nt
	global_load_dwordx4 v[104:107], v67, s[16:17] offset:128 nt
	global_load_dwordx4 v[108:111], v67, s[16:17] offset:144 nt
	global_load_dwordx4 v[112:115], v67, s[16:17] offset:160 nt
	global_load_dwordx4 v[116:119], v67, s[16:17] offset:176 nt
	global_load_dwordx4 v[120:123], v67, s[16:17] offset:192 nt
	global_load_dwordx4 v[124:127], v67, s[16:17] offset:208 nt
	global_load_dwordx4 v[128:131], v67, s[16:17] offset:224 nt
	global_load_dwordx4 v[132:135], v67, s[16:17] offset:240 nt
	v_mad_i64_i32 v[136:137], s[16:17], s13, v1, v[70:71]
	s_lshl_b64 s[16:17], s[14:15], 12
	s_add_u32 s16, s21, s16
	s_addc_u32 s17, s22, s17
	s_add_i32 s13, s14, s20
	s_or_b32 s12, s12, 7
	s_waitcnt vmcnt(15)
	v_fma_f32 v69, v14, v72, 0
	v_fmac_f32_e32 v69, v15, v73
	v_fmac_f32_e32 v69, v16, v74
	v_fmac_f32_e32 v69, v17, v75
	s_waitcnt vmcnt(14)
	v_fmac_f32_e32 v69, v10, v76
	v_fmac_f32_e32 v69, v11, v77
	v_fmac_f32_e32 v69, v12, v78
	v_fmac_f32_e32 v69, v13, v79
	s_waitcnt vmcnt(13)
	v_fmac_f32_e32 v69, v6, v80
	v_fmac_f32_e32 v69, v7, v81
	v_fmac_f32_e32 v69, v8, v82
	v_fmac_f32_e32 v69, v9, v83
	s_waitcnt vmcnt(12)
	v_fmac_f32_e32 v69, v2, v84
	v_fmac_f32_e32 v69, v3, v85
	v_fmac_f32_e32 v69, v4, v86
	v_fmac_f32_e32 v69, v5, v87
	s_waitcnt vmcnt(11)
	v_fmac_f32_e32 v69, v30, v88
	v_fmac_f32_e32 v69, v31, v89
	v_fmac_f32_e32 v69, v32, v90
	v_fmac_f32_e32 v69, v33, v91
	s_waitcnt vmcnt(10)
	v_fmac_f32_e32 v69, v26, v92
	v_fmac_f32_e32 v69, v27, v93
	v_fmac_f32_e32 v69, v28, v94
	v_fmac_f32_e32 v69, v29, v95
	s_waitcnt vmcnt(9)
	v_fmac_f32_e32 v69, v22, v96
	v_fmac_f32_e32 v69, v23, v97
	v_fmac_f32_e32 v69, v24, v98
	v_fmac_f32_e32 v69, v25, v99
	s_waitcnt vmcnt(8)
	v_fmac_f32_e32 v69, v18, v100
	v_fmac_f32_e32 v69, v19, v101
	v_fmac_f32_e32 v69, v20, v102
	v_fmac_f32_e32 v69, v21, v103
	s_waitcnt vmcnt(7)
	v_fmac_f32_e32 v69, v46, v104
	v_fmac_f32_e32 v69, v47, v105
	v_fmac_f32_e32 v69, v48, v106
	v_fmac_f32_e32 v69, v49, v107
	s_waitcnt vmcnt(6)
	v_fmac_f32_e32 v69, v42, v108
	v_fmac_f32_e32 v69, v43, v109
	v_fmac_f32_e32 v69, v44, v110
	v_fmac_f32_e32 v69, v45, v111
	s_waitcnt vmcnt(5)
	v_fmac_f32_e32 v69, v38, v112
	v_fmac_f32_e32 v69, v39, v113
	v_fmac_f32_e32 v69, v40, v114
	v_fmac_f32_e32 v69, v41, v115
	s_waitcnt vmcnt(4)
	v_fmac_f32_e32 v69, v34, v116
	v_fmac_f32_e32 v69, v35, v117
	v_fmac_f32_e32 v69, v36, v118
	v_fmac_f32_e32 v69, v37, v119
	s_waitcnt vmcnt(3)
	v_fmac_f32_e32 v69, v62, v120
	v_fmac_f32_e32 v69, v63, v121
	v_fmac_f32_e32 v69, v64, v122
	v_fmac_f32_e32 v69, v65, v123
	s_waitcnt vmcnt(2)
	v_fmac_f32_e32 v69, v58, v124
	v_fmac_f32_e32 v69, v59, v125
	v_fmac_f32_e32 v69, v60, v126
	v_fmac_f32_e32 v69, v61, v127
	s_waitcnt vmcnt(1)
	v_fmac_f32_e32 v69, v54, v128
	v_fmac_f32_e32 v69, v55, v129
	v_fmac_f32_e32 v69, v56, v130
	v_fmac_f32_e32 v69, v57, v131
	s_waitcnt vmcnt(0)
	v_fmac_f32_e32 v69, v50, v132
	v_fmac_f32_e32 v69, v51, v133
	v_fmac_f32_e32 v69, v52, v134
	v_fmac_f32_e32 v69, v53, v135
	v_mul_f32_e32 v69, v68, v69
	v_cvt_pk_bf16_f32 v69, v69, s0
	global_store_short v[136:137], v69, off
	global_load_dwordx4 v[72:75], v67, s[16:17] nt
	global_load_dwordx4 v[76:79], v67, s[16:17] offset:16 nt
	global_load_dwordx4 v[80:83], v67, s[16:17] offset:32 nt
	global_load_dwordx4 v[84:87], v67, s[16:17] offset:48 nt
	global_load_dwordx4 v[88:91], v67, s[16:17] offset:64 nt
	global_load_dwordx4 v[92:95], v67, s[16:17] offset:80 nt
	global_load_dwordx4 v[96:99], v67, s[16:17] offset:96 nt
	global_load_dwordx4 v[100:103], v67, s[16:17] offset:112 nt
	global_load_dwordx4 v[104:107], v67, s[16:17] offset:128 nt
	global_load_dwordx4 v[108:111], v67, s[16:17] offset:144 nt
	global_load_dwordx4 v[112:115], v67, s[16:17] offset:160 nt
	global_load_dwordx4 v[116:119], v67, s[16:17] offset:176 nt
	global_load_dwordx4 v[120:123], v67, s[16:17] offset:192 nt
	global_load_dwordx4 v[124:127], v67, s[16:17] offset:208 nt
	global_load_dwordx4 v[128:131], v67, s[16:17] offset:224 nt
	global_load_dwordx4 v[132:135], v67, s[16:17] offset:240 nt
	v_mad_i64_i32 v[136:137], s[14:15], s13, v1, v[70:71]
	s_ashr_i32 s13, s12, 31
	s_lshl_b64 s[14:15], s[12:13], 12
	s_add_u32 s14, s21, s14
	s_addc_u32 s15, s22, s15
	s_add_i32 s12, s12, s20
	s_waitcnt vmcnt(15)
	v_fma_f32 v69, v14, v72, 0
	v_fmac_f32_e32 v69, v15, v73
	v_fmac_f32_e32 v69, v16, v74
	v_fmac_f32_e32 v69, v17, v75
	s_waitcnt vmcnt(14)
	v_fmac_f32_e32 v69, v10, v76
	v_fmac_f32_e32 v69, v11, v77
	v_fmac_f32_e32 v69, v12, v78
	v_fmac_f32_e32 v69, v13, v79
	s_waitcnt vmcnt(13)
	v_fmac_f32_e32 v69, v6, v80
	v_fmac_f32_e32 v69, v7, v81
	v_fmac_f32_e32 v69, v8, v82
	v_fmac_f32_e32 v69, v9, v83
	s_waitcnt vmcnt(12)
	v_fmac_f32_e32 v69, v2, v84
	v_fmac_f32_e32 v69, v3, v85
	v_fmac_f32_e32 v69, v4, v86
	v_fmac_f32_e32 v69, v5, v87
	s_waitcnt vmcnt(11)
	v_fmac_f32_e32 v69, v30, v88
	v_fmac_f32_e32 v69, v31, v89
	v_fmac_f32_e32 v69, v32, v90
	v_fmac_f32_e32 v69, v33, v91
	s_waitcnt vmcnt(10)
	v_fmac_f32_e32 v69, v26, v92
	v_fmac_f32_e32 v69, v27, v93
	v_fmac_f32_e32 v69, v28, v94
	v_fmac_f32_e32 v69, v29, v95
	s_waitcnt vmcnt(9)
	v_fmac_f32_e32 v69, v22, v96
	v_fmac_f32_e32 v69, v23, v97
	v_fmac_f32_e32 v69, v24, v98
	v_fmac_f32_e32 v69, v25, v99
	s_waitcnt vmcnt(8)
	v_fmac_f32_e32 v69, v18, v100
	v_fmac_f32_e32 v69, v19, v101
	v_fmac_f32_e32 v69, v20, v102
	v_fmac_f32_e32 v69, v21, v103
	s_waitcnt vmcnt(7)
	v_fmac_f32_e32 v69, v46, v104
	v_fmac_f32_e32 v69, v47, v105
	v_fmac_f32_e32 v69, v48, v106
	v_fmac_f32_e32 v69, v49, v107
	s_waitcnt vmcnt(6)
	v_fmac_f32_e32 v69, v42, v108
	v_fmac_f32_e32 v69, v43, v109
	v_fmac_f32_e32 v69, v44, v110
	v_fmac_f32_e32 v69, v45, v111
	s_waitcnt vmcnt(5)
	v_fmac_f32_e32 v69, v38, v112
	v_fmac_f32_e32 v69, v39, v113
	v_fmac_f32_e32 v69, v40, v114
	v_fmac_f32_e32 v69, v41, v115
	s_waitcnt vmcnt(4)
	v_fmac_f32_e32 v69, v34, v116
	v_fmac_f32_e32 v69, v35, v117
	v_fmac_f32_e32 v69, v36, v118
	v_fmac_f32_e32 v69, v37, v119
	s_waitcnt vmcnt(3)
	v_fmac_f32_e32 v69, v62, v120
	v_fmac_f32_e32 v69, v63, v121
	v_fmac_f32_e32 v69, v64, v122
	v_fmac_f32_e32 v69, v65, v123
	s_waitcnt vmcnt(2)
	v_fmac_f32_e32 v69, v58, v124
	v_fmac_f32_e32 v69, v59, v125
	v_fmac_f32_e32 v69, v60, v126
	v_fmac_f32_e32 v69, v61, v127
	s_waitcnt vmcnt(1)
	v_fmac_f32_e32 v69, v54, v128
	v_fmac_f32_e32 v69, v55, v129
	v_fmac_f32_e32 v69, v56, v130
	v_fmac_f32_e32 v69, v57, v131
	s_waitcnt vmcnt(0)
	v_fmac_f32_e32 v69, v50, v132
	v_fmac_f32_e32 v69, v51, v133
	v_fmac_f32_e32 v69, v52, v134
	v_fmac_f32_e32 v69, v53, v135
	v_mul_f32_e32 v69, v68, v69
	v_cvt_pk_bf16_f32 v69, v69, s0
	global_store_short v[136:137], v69, off
	global_load_dwordx4 v[72:75], v67, s[14:15] nt
	global_load_dwordx4 v[76:79], v67, s[14:15] offset:16 nt
	global_load_dwordx4 v[80:83], v67, s[14:15] offset:32 nt
	global_load_dwordx4 v[84:87], v67, s[14:15] offset:48 nt
	global_load_dwordx4 v[88:91], v67, s[14:15] offset:64 nt
	global_load_dwordx4 v[92:95], v67, s[14:15] offset:80 nt
	global_load_dwordx4 v[96:99], v67, s[14:15] offset:96 nt
	global_load_dwordx4 v[100:103], v67, s[14:15] offset:112 nt
	global_load_dwordx4 v[104:107], v67, s[14:15] offset:128 nt
	global_load_dwordx4 v[108:111], v67, s[14:15] offset:144 nt
	global_load_dwordx4 v[112:115], v67, s[14:15] offset:160 nt
	global_load_dwordx4 v[116:119], v67, s[14:15] offset:176 nt
	global_load_dwordx4 v[120:123], v67, s[14:15] offset:192 nt
	global_load_dwordx4 v[124:127], v67, s[14:15] offset:208 nt
	global_load_dwordx4 v[128:131], v67, s[14:15] offset:224 nt
	global_load_dwordx4 v[132:135], v67, s[14:15] offset:240 nt
	s_waitcnt vmcnt(15)
	v_fma_f32 v14, v14, v72, 0
	v_fmac_f32_e32 v14, v15, v73
	v_fmac_f32_e32 v14, v16, v74
	v_fmac_f32_e32 v14, v17, v75
	s_waitcnt vmcnt(14)
	v_fmac_f32_e32 v14, v10, v76
	v_fmac_f32_e32 v14, v11, v77
	v_fmac_f32_e32 v14, v12, v78
	v_fmac_f32_e32 v14, v13, v79
	s_waitcnt vmcnt(13)
	v_fmac_f32_e32 v14, v6, v80
	v_fmac_f32_e32 v14, v7, v81
	v_fmac_f32_e32 v14, v8, v82
	v_fmac_f32_e32 v14, v9, v83
	s_waitcnt vmcnt(12)
	v_fmac_f32_e32 v14, v2, v84
	v_fmac_f32_e32 v14, v3, v85
	v_fmac_f32_e32 v14, v4, v86
	v_fmac_f32_e32 v14, v5, v87
	s_waitcnt vmcnt(11)
	v_fmac_f32_e32 v14, v30, v88
	v_fmac_f32_e32 v14, v31, v89
	v_fmac_f32_e32 v14, v32, v90
	v_fmac_f32_e32 v14, v33, v91
	s_waitcnt vmcnt(10)
	v_fmac_f32_e32 v14, v26, v92
	v_fmac_f32_e32 v14, v27, v93
	v_fmac_f32_e32 v14, v28, v94
	v_fmac_f32_e32 v14, v29, v95
	s_waitcnt vmcnt(9)
	v_fmac_f32_e32 v14, v22, v96
	v_fmac_f32_e32 v14, v23, v97
	v_fmac_f32_e32 v14, v24, v98
	v_fmac_f32_e32 v14, v25, v99
	s_waitcnt vmcnt(8)
	v_fmac_f32_e32 v14, v18, v100
	v_fmac_f32_e32 v14, v19, v101
	v_fmac_f32_e32 v14, v20, v102
	v_fmac_f32_e32 v14, v21, v103
	s_waitcnt vmcnt(7)
	v_fmac_f32_e32 v14, v46, v104
	v_fmac_f32_e32 v14, v47, v105
	v_fmac_f32_e32 v14, v48, v106
	v_fmac_f32_e32 v14, v49, v107
	s_waitcnt vmcnt(6)
	v_fmac_f32_e32 v14, v42, v108
	v_fmac_f32_e32 v14, v43, v109
	v_fmac_f32_e32 v14, v44, v110
	v_fmac_f32_e32 v14, v45, v111
	s_waitcnt vmcnt(5)
	v_fmac_f32_e32 v14, v38, v112
	v_fmac_f32_e32 v14, v39, v113
	v_fmac_f32_e32 v14, v40, v114
	v_fmac_f32_e32 v14, v41, v115
	s_waitcnt vmcnt(4)
	v_fmac_f32_e32 v14, v34, v116
	v_fmac_f32_e32 v14, v35, v117
	v_fmac_f32_e32 v14, v36, v118
	v_fmac_f32_e32 v14, v37, v119
	s_waitcnt vmcnt(3)
	v_fmac_f32_e32 v14, v62, v120
	v_fmac_f32_e32 v14, v63, v121
	v_fmac_f32_e32 v14, v64, v122
	v_fmac_f32_e32 v14, v65, v123
	s_waitcnt vmcnt(2)
	v_fmac_f32_e32 v14, v58, v124
	v_fmac_f32_e32 v14, v59, v125
	v_fmac_f32_e32 v14, v60, v126
	v_fmac_f32_e32 v14, v61, v127
	s_waitcnt vmcnt(1)
	v_fmac_f32_e32 v14, v54, v128
	v_fmac_f32_e32 v14, v55, v129
	v_fmac_f32_e32 v14, v56, v130
	v_fmac_f32_e32 v14, v57, v131
	s_waitcnt vmcnt(0)
	v_fmac_f32_e32 v14, v50, v132
	v_fmac_f32_e32 v14, v51, v133
	v_fmac_f32_e32 v14, v52, v134
	v_fmac_f32_e32 v14, v53, v135
	v_mul_f32_e32 v2, v68, v14
	v_cvt_pk_bf16_f32 v4, v2, s0
	v_mad_i64_i32 v[2:3], s[12:13], s12, v1, v[70:71]
	global_store_short v[2:3], v4, off
	s_branch .LBB0_179
